# v25 + EpiMixPair epilogue: the vmcnt(0) after each half's gate-load batch replaced by counted waits per (m,bj) group (valid for both the alt-0 and alt-1 paths)
# speedup vs baseline: 1.0051x; 1.0051x over previous
; __device__ __forceinline__ u32x4 pack8(const f32x4 a, const f32x4 b) { u32x4 w; w.x = cvt_pk_bf16(a[0], a[1]); w.y = cvt_pk_bf16(a[2], a[3]); w.z = cvt_pk_bf16(b[0], b[1]); w.w = cvt_pk_bf16(b[2], b[3]); return w; }
; __device__ __forceinline__ void unpack8(const u32x4 w, f32x4& a, f32x4& b) { a = (f32x4){bflo(w.x), bfhi(w.x), bflo(w.y), bfhi(w.y)}; b = (f32x4){bflo(w.z), bfhi(w.z), bflo(w.w), bfhi(w.w)}; }
; __device__ __forceinline__ f32x4 sig4(const f32x4 v) { return (f32x4){sigmoidf_(v[0]), sigmoidf_(v[1]), sigmoidf_(v[2]), sigmoidf_(v[3])}; }
;     __device__ __forceinline__ void operator()(Acc& acc, const Unit& u, int wr, int wc, int fr, int fq) const {
;     ...
;             for (int m = 0; m < 4; ++m)
; #pragma unroll
;                 for (int bj = 0; bj < 2; ++bj) { f32x4 b0, b1; unpack8(bv[m][bj], b0, b1);
;                     if (u.alt == 0) { f32x4 a0, a1; unpack8(av[m][bj], a0, a1);
; #pragma unroll
;                         for (int r = 0; r < 4; ++r) { acc[ai][bj][m][0][r] *= (1.0f + __expf(-b0[r])) * __builtin_amdgcn_rcpf(1.0f + __expf(-a0[r]));
;                                                       acc[ai][bj][m][1][r] *= (1.0f + __expf(-b1[r])) * __builtin_amdgcn_rcpf(1.0f + __expf(-a1[r])); } }
;                     else *(u32x4*)(mixed + (size_t)(row0 + ai * 128 + m * 16) * 1024 + col0 + bj * 128) = pack8(acc[ai][bj][m][0] * sig4(b0), acc[ai][bj][m][1] * sig4(b1)); } }
.LBB0_274:
	v_lshlrev_b64 v[222:223], 11, v[214:215]
	s_waitcnt vmcnt(7)
	v_lshlrev_b32_e32 v0, 16, v192
	v_and_b32_e32 v192, 0xffff0000, v192
	v_lshlrev_b32_e32 v215, 16, v193
	v_and_b32_e32 v193, 0xffff0000, v193
	v_lshlrev_b32_e32 v217, 16, v194
	v_and_b32_e32 v194, 0xffff0000, v194
	v_lshlrev_b32_e32 v219, 16, v195
	v_and_b32_e32 v195, 0xffff0000, v195
	v_mul_f32_e32 v0, 0xbfb8aa3b, v0
	v_mul_f32_e32 v221, 0xbfb8aa3b, v192
	v_mul_f32_e32 v215, 0xbfb8aa3b, v215
	v_mul_f32_e32 v227, 0xbfb8aa3b, v193
	v_mul_f32_e32 v217, 0xbfb8aa3b, v217
	v_mul_f32_e32 v243, 0xbfb8aa3b, v194
	v_mul_f32_e32 v219, 0xbfb8aa3b, v219
	v_mul_f32_e32 v244, 0xbfb8aa3b, v195
	v_lshl_add_u64 v[192:193], s[6:7], 0, v[222:223]
	v_exp_f32_e32 v224, v0
	v_exp_f32_e32 v225, v221
	v_exp_f32_e32 v226, v215
	v_exp_f32_e32 v227, v227
	v_exp_f32_e32 v194, v217
	v_exp_f32_e32 v195, v243
	v_exp_f32_e32 v222, v219
	v_exp_f32_e32 v223, v244
	s_mov_b64 s[42:43], -1
	s_and_b64 vcc, exec, s[64:65]
	v_lshl_add_u64 v[192:193], v[2:3], 1, v[192:193]
	s_cbranch_vccz .LBB0_276
	v_add_f32_e32 v0, 1.0, v224
	v_rcp_f32_e32 v244, v0
	v_add_f32_e32 v0, 1.0, v225
	v_rcp_f32_e32 v245, v0
	v_add_f32_e32 v0, 1.0, v226
	v_rcp_f32_e32 v246, v0
	v_add_f32_e32 v0, 1.0, v227
	v_rcp_f32_e32 v247, v0
	v_add_f32_e32 v0, 1.0, v194
	v_add_f32_e32 v215, 1.0, v222
	v_rcp_f32_e32 v248, v0
	v_add_f32_e32 v0, 1.0, v195
	v_rcp_f32_e32 v250, v215
	v_add_f32_e32 v215, 1.0, v223
	v_rcp_f32_e32 v251, v215
	v_rcp_f32_e32 v249, v0
	v_pk_mul_f32 v[246:247], v[6:7], v[246:247]
	v_pk_mul_f32 v[244:245], v[4:5], v[244:245]
	v_pk_mul_f32 v[250:251], v[10:11], v[250:251]
	v_pk_mul_f32 v[248:249], v[8:9], v[248:249]
	v_cvt_pk_bf16_f32 v244, v244, v245
	v_cvt_pk_bf16_f32 v245, v246, v247
	v_cvt_pk_bf16_f32 v246, v248, v249
	v_cvt_pk_bf16_f32 v247, v250, v251
	global_store_dwordx4 v[192:193], v[244:247], off
	s_mov_b64 s[42:43], 0
.LBB0_276:
	s_andn2_b64 vcc, exec, s[42:43]
	s_cbranch_vccnz .LBB0_278
	s_waitcnt vmcnt(14)
	v_lshlrev_b32_e32 v0, 16, v160
	v_lshlrev_b32_e32 v221, 16, v162
	v_mul_f32_e32 v0, 0xbfb8aa3b, v0
	v_and_b32_e32 v215, 0xffff0000, v160
	v_exp_f32_e32 v0, v0
	v_mul_f32_e32 v221, 0xbfb8aa3b, v221
	v_exp_f32_e32 v221, v221
	v_mul_f32_e32 v215, 0xbfb8aa3b, v215
	v_exp_f32_e32 v215, v215
	v_add_f32_e32 v0, 1.0, v0
	v_and_b32_e32 v243, 0xffff0000, v162
	v_rcp_f32_e32 v244, v0
	v_add_f32_e32 v0, 1.0, v221
	v_lshlrev_b32_e32 v217, 16, v161
	v_rcp_f32_e32 v246, v0
	v_add_f32_e32 v0, 1.0, v215
	v_mul_f32_e32 v215, 0xbfb8aa3b, v243
	v_exp_f32_e32 v215, v215
	v_mul_f32_e32 v217, 0xbfb8aa3b, v217
	v_exp_f32_e32 v217, v217
	v_lshlrev_b32_e32 v248, 16, v163
	v_and_b32_e32 v219, 0xffff0000, v161
	v_rcp_f32_e32 v245, v0
	v_add_f32_e32 v0, 1.0, v215
	v_mul_f32_e32 v215, 0xbfb8aa3b, v248
	v_rcp_f32_e32 v247, v0
	v_add_f32_e32 v0, 1.0, v217
	v_exp_f32_e32 v215, v215
	v_mul_f32_e32 v217, 0xbfb8aa3b, v219
	v_exp_f32_e32 v217, v217
	v_rcp_f32_e32 v248, v0
	v_add_f32_e32 v0, 1.0, v215
	v_and_b32_e32 v251, 0xffff0000, v163
	v_rcp_f32_e32 v250, v0
	v_add_f32_e32 v0, 1.0, v217
	v_rcp_f32_e32 v249, v0
	v_mul_f32_e32 v0, 0xbfb8aa3b, v251
	v_exp_f32_e32 v0, v0
	v_pk_add_f32 v[226:227], v[226:227], 1.0 op_sel_hi:[1,0]
	v_pk_add_f32 v[224:225], v[224:225], 1.0 op_sel_hi:[1,0]
	v_pk_add_f32 v[222:223], v[222:223], 1.0 op_sel_hi:[1,0]
	v_add_f32_e32 v0, 1.0, v0
	v_rcp_f32_e32 v251, v0
	v_pk_add_f32 v[194:195], v[194:195], 1.0 op_sel_hi:[1,0]
	v_pk_mul_f32 v[224:225], v[224:225], v[244:245]
	v_pk_mul_f32 v[226:227], v[226:227], v[248:249]
	v_pk_mul_f32 v[194:195], v[194:195], v[246:247]
	v_pk_mul_f32 v[222:223], v[222:223], v[250:251]
	v_pk_mul_f32 v[6:7], v[6:7], v[226:227]
	v_pk_mul_f32 v[4:5], v[4:5], v[224:225]
	v_pk_mul_f32 v[10:11], v[10:11], v[222:223]
	v_pk_mul_f32 v[8:9], v[8:9], v[194:195]
.LBB0_278:
	s_waitcnt vmcnt(7)
	v_lshlrev_b32_e32 v0, 16, v188
	v_and_b32_e32 v188, 0xffff0000, v188
	v_lshlrev_b32_e32 v194, 16, v189
	v_and_b32_e32 v189, 0xffff0000, v189
	v_lshlrev_b32_e32 v195, 16, v190
	v_and_b32_e32 v190, 0xffff0000, v190
	v_lshlrev_b32_e32 v215, 16, v191
	v_and_b32_e32 v191, 0xffff0000, v191
	v_cndmask_b32_e64 v217, 0, 1, s[64:65]
	v_cmp_ne_u32_e64 s[42:43], 1, v217
	v_mul_f32_e32 v0, 0xbfb8aa3b, v0
	v_mul_f32_e32 v188, 0xbfb8aa3b, v188
	v_mul_f32_e32 v217, 0xbfb8aa3b, v194
	v_mul_f32_e32 v189, 0xbfb8aa3b, v189
	v_mul_f32_e32 v219, 0xbfb8aa3b, v195
	v_mul_f32_e32 v190, 0xbfb8aa3b, v190
	v_mul_f32_e32 v215, 0xbfb8aa3b, v215
	v_mul_f32_e32 v191, 0xbfb8aa3b, v191
	v_exp_f32_e32 v194, v0
	v_exp_f32_e32 v195, v188
	v_exp_f32_e32 v222, v217
	v_exp_f32_e32 v223, v189
	v_exp_f32_e32 v188, v219
	v_exp_f32_e32 v189, v190
	v_exp_f32_e32 v190, v215
	v_exp_f32_e32 v191, v191
	s_mov_b64 s[66:67], -1
	s_andn2_b64 vcc, exec, s[64:65]
	s_cbranch_vccnz .LBB0_280
	v_add_f32_e32 v0, 1.0, v194
	v_rcp_f32_e32 v224, v0
	v_add_f32_e32 v0, 1.0, v195
	v_rcp_f32_e32 v225, v0
	v_add_f32_e32 v0, 1.0, v222
	v_rcp_f32_e32 v226, v0
	v_add_f32_e32 v0, 1.0, v223
	v_rcp_f32_e32 v227, v0
	v_add_f32_e32 v0, 1.0, v188
	v_add_f32_e32 v215, 1.0, v190
	v_rcp_f32_e32 v244, v0
	v_add_f32_e32 v0, 1.0, v189
	v_rcp_f32_e32 v246, v215
	v_add_f32_e32 v215, 1.0, v191
	v_rcp_f32_e32 v247, v215
	v_rcp_f32_e32 v245, v0
	v_pk_mul_f32 v[226:227], v[106:107], v[226:227]
	v_pk_mul_f32 v[224:225], v[104:105], v[224:225]
	v_pk_mul_f32 v[246:247], v[102:103], v[246:247]
	v_pk_mul_f32 v[244:245], v[100:101], v[244:245]
	v_cvt_pk_bf16_f32 v224, v224, v225
	v_cvt_pk_bf16_f32 v225, v226, v227
	v_cvt_pk_bf16_f32 v226, v244, v245
	v_cvt_pk_bf16_f32 v227, v246, v247
	s_mov_b64 s[66:67], 0
	global_store_dwordx4 v[192:193], v[224:227], off offset:256
; __device__ __forceinline__ u32x4 pack8(const f32x4 a, const f32x4 b) { u32x4 w; w.x = cvt_pk_bf16(a[0], a[1]); w.y = cvt_pk_bf16(a[2], a[3]); w.z = cvt_pk_bf16(b[0], b[1]); w.w = cvt_pk_bf16(b[2], b[3]); return w; }
; __device__ __forceinline__ void unpack8(const u32x4 w, f32x4& a, f32x4& b) { a = (f32x4){bflo(w.x), bfhi(w.x), bflo(w.y), bfhi(w.y)}; b = (f32x4){bflo(w.z), bfhi(w.z), bflo(w.w), bfhi(w.w)}; }
; __device__ __forceinline__ f32x4 sig4(const f32x4 v) { return (f32x4){sigmoidf_(v[0]), sigmoidf_(v[1]), sigmoidf_(v[2]), sigmoidf_(v[3])}; }
;     __device__ __forceinline__ void operator()(Acc& acc, const Unit& u, int wr, int wc, int fr, int fq) const {
;     ...
;             for (int m = 0; m < 4; ++m)
; #pragma unroll
;                 for (int bj = 0; bj < 2; ++bj) { f32x4 b0, b1; unpack8(bv[m][bj], b0, b1);
;                     if (u.alt == 0) { f32x4 a0, a1; unpack8(av[m][bj], a0, a1);
; #pragma unroll
;                         for (int r = 0; r < 4; ++r) { acc[ai][bj][m][0][r] *= (1.0f + __expf(-b0[r])) * __builtin_amdgcn_rcpf(1.0f + __expf(-a0[r]));
;                                                       acc[ai][bj][m][1][r] *= (1.0f + __expf(-b1[r])) * __builtin_amdgcn_rcpf(1.0f + __expf(-a1[r])); } }
;                     else *(u32x4*)(mixed + (size_t)(row0 + ai * 128 + m * 16) * 1024 + col0 + bj * 128) = pack8(acc[ai][bj][m][0] * sig4(b0), acc[ai][bj][m][1] * sig4(b1)); } }
.LBB0_280:
	s_andn2_b64 vcc, exec, s[66:67]
	s_cbranch_vccnz .LBB0_282
	s_waitcnt vmcnt(12)
	v_lshlrev_b32_e32 v0, 16, v156
	v_lshlrev_b32_e32 v217, 16, v158
	v_mul_f32_e32 v0, 0xbfb8aa3b, v0
	v_exp_f32_e32 v0, v0
	v_mul_f32_e32 v217, 0xbfb8aa3b, v217
	v_exp_f32_e32 v217, v217
	v_and_b32_e32 v192, 0xffff0000, v156
	v_and_b32_e32 v219, 0xffff0000, v158
	v_add_f32_e32 v0, 1.0, v0
	v_mul_f32_e32 v192, 0xbfb8aa3b, v192
	v_exp_f32_e32 v225, v192
	v_rcp_f32_e32 v192, v0
	v_add_f32_e32 v0, 1.0, v217
	v_mul_f32_e32 v217, 0xbfb8aa3b, v219
	v_exp_f32_e32 v217, v217
	v_lshlrev_b32_e32 v193, 16, v157
	v_lshlrev_b32_e32 v221, 16, v159
	v_rcp_f32_e32 v224, v0
	v_add_f32_e32 v0, 1.0, v225
	v_mul_f32_e32 v193, 0xbfb8aa3b, v193
	v_and_b32_e32 v215, 0xffff0000, v157
	v_exp_f32_e32 v219, v193
	v_rcp_f32_e32 v193, v0
	v_add_f32_e32 v0, 1.0, v217
	v_mul_f32_e32 v217, 0xbfb8aa3b, v221
	v_exp_f32_e32 v217, v217
	v_mul_f32_e32 v215, 0xbfb8aa3b, v215
	v_exp_f32_e32 v215, v215
	v_rcp_f32_e32 v225, v0
	v_add_f32_e32 v0, 1.0, v219
	v_rcp_f32_e32 v226, v0
	v_add_f32_e32 v0, 1.0, v217
	v_and_b32_e32 v243, 0xffff0000, v159
	v_rcp_f32_e32 v244, v0
	v_add_f32_e32 v0, 1.0, v215
	v_rcp_f32_e32 v227, v0
	v_mul_f32_e32 v0, 0xbfb8aa3b, v243
	v_exp_f32_e32 v0, v0
	v_pk_add_f32 v[222:223], v[222:223], 1.0 op_sel_hi:[1,0]
	v_pk_add_f32 v[194:195], v[194:195], 1.0 op_sel_hi:[1,0]
	v_pk_add_f32 v[190:191], v[190:191], 1.0 op_sel_hi:[1,0]
	v_add_f32_e32 v0, 1.0, v0
	v_rcp_f32_e32 v245, v0
	v_pk_add_f32 v[188:189], v[188:189], 1.0 op_sel_hi:[1,0]
	v_pk_mul_f32 v[192:193], v[194:195], v[192:193]
	v_pk_mul_f32 v[194:195], v[222:223], v[226:227]
	v_pk_mul_f32 v[188:189], v[188:189], v[224:225]
	v_pk_mul_f32 v[190:191], v[190:191], v[244:245]
	v_pk_mul_f32 v[106:107], v[106:107], v[194:195]
	v_pk_mul_f32 v[104:105], v[104:105], v[192:193]
	v_pk_mul_f32 v[102:103], v[102:103], v[190:191]
	v_pk_mul_f32 v[100:101], v[100:101], v[188:189]
.LBB0_282:
	s_waitcnt vmcnt(7)
	v_lshlrev_b32_e32 v0, 16, v184
	v_and_b32_e32 v184, 0xffff0000, v184
	v_lshlrev_b32_e32 v188, 16, v185
	v_and_b32_e32 v185, 0xffff0000, v185
	v_lshlrev_b32_e32 v189, 16, v186
	v_and_b32_e32 v186, 0xffff0000, v186
	v_lshlrev_b32_e32 v190, 16, v187
	v_and_b32_e32 v187, 0xffff0000, v187
	v_mul_f32_e32 v0, 0xbfb8aa3b, v0
	v_mul_f32_e32 v184, 0xbfb8aa3b, v184
	v_mul_f32_e32 v188, 0xbfb8aa3b, v188
	v_mul_f32_e32 v185, 0xbfb8aa3b, v185
	v_mul_f32_e32 v189, 0xbfb8aa3b, v189
	v_mul_f32_e32 v215, 0xbfb8aa3b, v186
	v_mul_f32_e32 v217, 0xbfb8aa3b, v190
	v_mul_f32_e32 v219, 0xbfb8aa3b, v187
	v_ashrrev_i32_e32 v221, 31, v220
	v_exp_f32_e32 v190, v0
	v_exp_f32_e32 v191, v184
	v_exp_f32_e32 v192, v188
	v_exp_f32_e32 v193, v185
	v_exp_f32_e32 v186, v189
	v_exp_f32_e32 v187, v215
	v_exp_f32_e32 v188, v217
	v_exp_f32_e32 v189, v219
	v_lshlrev_b64 v[194:195], 11, v[220:221]
	v_lshl_add_u64 v[184:185], s[6:7], 0, v[194:195]
	s_mov_b64 s[64:65], -1
	s_and_b64 vcc, exec, s[42:43]
	v_lshl_add_u64 v[184:185], v[2:3], 1, v[184:185]
	s_cbranch_vccnz .LBB0_284
	v_add_f32_e32 v0, 1.0, v190
	v_rcp_f32_e32 v194, v0
	v_add_f32_e32 v0, 1.0, v191
	v_rcp_f32_e32 v195, v0
	v_add_f32_e32 v0, 1.0, v192
	v_rcp_f32_e32 v220, v0
	v_add_f32_e32 v0, 1.0, v193
	v_rcp_f32_e32 v221, v0
	v_add_f32_e32 v0, 1.0, v186
	v_add_f32_e32 v215, 1.0, v188
	v_rcp_f32_e32 v222, v0
	v_add_f32_e32 v0, 1.0, v187
	v_rcp_f32_e32 v224, v215
	v_add_f32_e32 v215, 1.0, v189
	v_rcp_f32_e32 v225, v215
	v_rcp_f32_e32 v223, v0
	v_pk_mul_f32 v[226:227], v[130:131], v[220:221]
	v_pk_mul_f32 v[194:195], v[128:129], v[194:195]
	v_pk_mul_f32 v[224:225], v[126:127], v[224:225]
	v_pk_mul_f32 v[222:223], v[124:125], v[222:223]
	v_cvt_pk_bf16_f32 v220, v194, v195
	v_cvt_pk_bf16_f32 v221, v226, v227
	v_cvt_pk_bf16_f32 v222, v222, v223
	v_cvt_pk_bf16_f32 v223, v224, v225
	s_mov_b64 s[64:65], 0
	global_store_dwordx4 v[184:185], v[220:223], off
.LBB0_284:
	s_andn2_b64 vcc, exec, s[64:65]
	s_cbranch_vccnz .LBB0_286
	s_waitcnt vmcnt(10)
	v_lshlrev_b32_e32 v0, 16, v152
	v_lshlrev_b32_e32 v217, 16, v154
	v_mul_f32_e32 v0, 0xbfb8aa3b, v0
	v_exp_f32_e32 v0, v0
	v_mul_f32_e32 v217, 0xbfb8aa3b, v217
	v_exp_f32_e32 v217, v217
	v_and_b32_e32 v194, 0xffff0000, v152
	v_and_b32_e32 v219, 0xffff0000, v154
	v_add_f32_e32 v0, 1.0, v0
	v_mul_f32_e32 v194, 0xbfb8aa3b, v194
	v_exp_f32_e32 v221, v194
	v_rcp_f32_e32 v194, v0
	v_add_f32_e32 v0, 1.0, v217
	v_mul_f32_e32 v217, 0xbfb8aa3b, v219
	v_exp_f32_e32 v217, v217
	v_lshlrev_b32_e32 v195, 16, v153
	v_lshlrev_b32_e32 v222, 16, v155
	v_rcp_f32_e32 v220, v0
	v_add_f32_e32 v0, 1.0, v221
	v_mul_f32_e32 v195, 0xbfb8aa3b, v195
	v_and_b32_e32 v215, 0xffff0000, v153
	v_exp_f32_e32 v219, v195
	v_rcp_f32_e32 v195, v0
	v_add_f32_e32 v0, 1.0, v217
	v_mul_f32_e32 v217, 0xbfb8aa3b, v222
	v_exp_f32_e32 v217, v217
	v_mul_f32_e32 v215, 0xbfb8aa3b, v215
	v_exp_f32_e32 v215, v215
	v_rcp_f32_e32 v221, v0
	v_add_f32_e32 v0, 1.0, v219
	v_rcp_f32_e32 v222, v0
	v_add_f32_e32 v0, 1.0, v217
	v_and_b32_e32 v225, 0xffff0000, v155
	v_rcp_f32_e32 v224, v0
	v_add_f32_e32 v0, 1.0, v215
	v_rcp_f32_e32 v223, v0
	v_mul_f32_e32 v0, 0xbfb8aa3b, v225
	v_exp_f32_e32 v0, v0
	v_pk_add_f32 v[192:193], v[192:193], 1.0 op_sel_hi:[1,0]
	v_pk_add_f32 v[190:191], v[190:191], 1.0 op_sel_hi:[1,0]
	v_pk_add_f32 v[188:189], v[188:189], 1.0 op_sel_hi:[1,0]
	v_add_f32_e32 v0, 1.0, v0
	v_rcp_f32_e32 v225, v0
	v_pk_add_f32 v[186:187], v[186:187], 1.0 op_sel_hi:[1,0]
	v_pk_mul_f32 v[190:191], v[190:191], v[194:195]
	v_pk_mul_f32 v[192:193], v[192:193], v[222:223]
	v_pk_mul_f32 v[186:187], v[186:187], v[220:221]
	v_pk_mul_f32 v[188:189], v[188:189], v[224:225]
	v_pk_mul_f32 v[130:131], v[130:131], v[192:193]
	v_pk_mul_f32 v[128:129], v[128:129], v[190:191]
	v_pk_mul_f32 v[126:127], v[126:127], v[188:189]
	v_pk_mul_f32 v[124:125], v[124:125], v[186:187]
; __device__ __forceinline__ u32x4 pack8(const f32x4 a, const f32x4 b) { u32x4 w; w.x = cvt_pk_bf16(a[0], a[1]); w.y = cvt_pk_bf16(a[2], a[3]); w.z = cvt_pk_bf16(b[0], b[1]); w.w = cvt_pk_bf16(b[2], b[3]); return w; }
; __device__ __forceinline__ void unpack8(const u32x4 w, f32x4& a, f32x4& b) { a = (f32x4){bflo(w.x), bfhi(w.x), bflo(w.y), bfhi(w.y)}; b = (f32x4){bflo(w.z), bfhi(w.z), bflo(w.w), bfhi(w.w)}; }
; __device__ __forceinline__ f32x4 sig4(const f32x4 v) { return (f32x4){sigmoidf_(v[0]), sigmoidf_(v[1]), sigmoidf_(v[2]), sigmoidf_(v[3])}; }
;     __device__ __forceinline__ void operator()(Acc& acc, const Unit& u, int wr, int wc, int fr, int fq) const {
;     ...
;             for (int m = 0; m < 4; ++m)
; #pragma unroll
;                 for (int bj = 0; bj < 2; ++bj) { f32x4 b0, b1; unpack8(bv[m][bj], b0, b1);
;                     if (u.alt == 0) { f32x4 a0, a1; unpack8(av[m][bj], a0, a1);
; #pragma unroll
;                         for (int r = 0; r < 4; ++r) { acc[ai][bj][m][0][r] *= (1.0f + __expf(-b0[r])) * __builtin_amdgcn_rcpf(1.0f + __expf(-a0[r]));
;                                                       acc[ai][bj][m][1][r] *= (1.0f + __expf(-b1[r])) * __builtin_amdgcn_rcpf(1.0f + __expf(-a1[r])); } }
;                     else *(u32x4*)(mixed + (size_t)(row0 + ai * 128 + m * 16) * 1024 + col0 + bj * 128) = pack8(acc[ai][bj][m][0] * sig4(b0), acc[ai][bj][m][1] * sig4(b1)); } }
.LBB0_286:
	s_waitcnt vmcnt(7)
	v_lshlrev_b32_e32 v0, 16, v180
	v_and_b32_e32 v180, 0xffff0000, v180
	v_lshlrev_b32_e32 v186, 16, v181
	v_and_b32_e32 v181, 0xffff0000, v181
	v_lshlrev_b32_e32 v187, 16, v182
	v_and_b32_e32 v182, 0xffff0000, v182
	v_lshlrev_b32_e32 v188, 16, v183
	v_and_b32_e32 v183, 0xffff0000, v183
	v_mul_f32_e32 v0, 0xbfb8aa3b, v0
	v_mul_f32_e32 v180, 0xbfb8aa3b, v180
	v_mul_f32_e32 v189, 0xbfb8aa3b, v186
	v_mul_f32_e32 v181, 0xbfb8aa3b, v181
	v_mul_f32_e32 v190, 0xbfb8aa3b, v187
	v_mul_f32_e32 v182, 0xbfb8aa3b, v182
	v_mul_f32_e32 v191, 0xbfb8aa3b, v188
	v_mul_f32_e32 v183, 0xbfb8aa3b, v183
	v_exp_f32_e32 v186, v0
	v_exp_f32_e32 v187, v180
	v_exp_f32_e32 v188, v189
	v_exp_f32_e32 v189, v181
	v_exp_f32_e32 v180, v190
	v_exp_f32_e32 v181, v182
	v_exp_f32_e32 v182, v191
	v_exp_f32_e32 v183, v183
	s_and_b64 vcc, exec, s[42:43]
	s_mov_b64 s[64:65], -1
	s_cbranch_vccnz .LBB0_288
	v_add_f32_e32 v0, 1.0, v186
	v_rcp_f32_e32 v190, v0
	v_add_f32_e32 v0, 1.0, v187
	v_rcp_f32_e32 v191, v0
	v_add_f32_e32 v0, 1.0, v188
	v_rcp_f32_e32 v192, v0
	v_add_f32_e32 v0, 1.0, v189
	v_rcp_f32_e32 v193, v0
	v_add_f32_e32 v0, 1.0, v180
	v_add_f32_e32 v195, 1.0, v182
	v_rcp_f32_e32 v194, v0
	v_add_f32_e32 v0, 1.0, v181
	v_rcp_f32_e32 v220, v195
	v_add_f32_e32 v195, 1.0, v183
	v_rcp_f32_e32 v221, v195
	v_rcp_f32_e32 v195, v0
	v_pk_mul_f32 v[192:193], v[98:99], v[192:193]
	v_pk_mul_f32 v[190:191], v[96:97], v[190:191]
	v_pk_mul_f32 v[220:221], v[94:95], v[220:221]
	v_pk_mul_f32 v[194:195], v[92:93], v[194:195]
	v_cvt_pk_bf16_f32 v190, v190, v191
	v_cvt_pk_bf16_f32 v191, v192, v193
	v_cvt_pk_bf16_f32 v192, v194, v195
	v_cvt_pk_bf16_f32 v193, v220, v221
	s_mov_b64 s[64:65], 0
	global_store_dwordx4 v[184:185], v[190:193], off offset:256
.LBB0_288:
	s_andn2_b64 vcc, exec, s[64:65]
	s_cbranch_vccnz .LBB0_290
	s_waitcnt vmcnt(8)
	v_lshlrev_b32_e32 v0, 16, v148
	v_lshlrev_b32_e32 v190, 16, v150
	v_mul_f32_e32 v0, 0xbfb8aa3b, v0
	v_and_b32_e32 v184, 0xffff0000, v148
	v_exp_f32_e32 v0, v0
	v_mul_f32_e32 v190, 0xbfb8aa3b, v190
	v_exp_f32_e32 v190, v190
	v_mul_f32_e32 v184, 0xbfb8aa3b, v184
	v_exp_f32_e32 v194, v184
	v_and_b32_e32 v191, 0xffff0000, v150
	v_lshlrev_b32_e32 v185, 16, v149
	v_add_f32_e32 v0, 1.0, v0
	v_mul_f32_e32 v191, 0xbfb8aa3b, v191
	v_lshlrev_b32_e32 v193, 16, v151
	v_rcp_f32_e32 v184, v0
	v_add_f32_e32 v0, 1.0, v190
	v_exp_f32_e32 v191, v191
	v_mul_f32_e32 v185, 0xbfb8aa3b, v185
	v_and_b32_e32 v192, 0xffff0000, v149
	v_rcp_f32_e32 v190, v0
	v_add_f32_e32 v0, 1.0, v194
	v_exp_f32_e32 v194, v185
	v_mul_f32_e32 v193, 0xbfb8aa3b, v193
	v_exp_f32_e32 v193, v193
	v_mul_f32_e32 v192, 0xbfb8aa3b, v192
	v_exp_f32_e32 v215, v192
	v_rcp_f32_e32 v185, v0
	v_add_f32_e32 v0, 1.0, v191
	v_rcp_f32_e32 v191, v0
	v_add_f32_e32 v0, 1.0, v194
	v_rcp_f32_e32 v192, v0
	v_add_f32_e32 v0, 1.0, v193
	v_and_b32_e32 v195, 0xffff0000, v151
	v_rcp_f32_e32 v194, v0
	v_add_f32_e32 v0, 1.0, v215
	v_rcp_f32_e32 v193, v0
	v_mul_f32_e32 v0, 0xbfb8aa3b, v195
	v_exp_f32_e32 v0, v0
	v_pk_add_f32 v[188:189], v[188:189], 1.0 op_sel_hi:[1,0]
	v_pk_add_f32 v[186:187], v[186:187], 1.0 op_sel_hi:[1,0]
	v_pk_add_f32 v[182:183], v[182:183], 1.0 op_sel_hi:[1,0]
	v_add_f32_e32 v0, 1.0, v0
	v_rcp_f32_e32 v195, v0
	v_pk_add_f32 v[180:181], v[180:181], 1.0 op_sel_hi:[1,0]
	v_pk_mul_f32 v[184:185], v[186:187], v[184:185]
	v_pk_mul_f32 v[186:187], v[188:189], v[192:193]
	v_pk_mul_f32 v[180:181], v[180:181], v[190:191]
	v_pk_mul_f32 v[182:183], v[182:183], v[194:195]
	v_pk_mul_f32 v[98:99], v[98:99], v[186:187]
	v_pk_mul_f32 v[96:97], v[96:97], v[184:185]
	v_pk_mul_f32 v[94:95], v[94:95], v[182:183]
	v_pk_mul_f32 v[92:93], v[92:93], v[180:181]
.LBB0_290:
	s_waitcnt vmcnt(7)
	v_lshlrev_b32_e32 v0, 16, v176
	v_and_b32_e32 v176, 0xffff0000, v176
	v_lshlrev_b32_e32 v180, 16, v177
	v_and_b32_e32 v177, 0xffff0000, v177
	v_lshlrev_b32_e32 v181, 16, v178
	v_and_b32_e32 v178, 0xffff0000, v178
	v_lshlrev_b32_e32 v182, 16, v179
	v_and_b32_e32 v179, 0xffff0000, v179
	v_mul_f32_e32 v0, 0xbfb8aa3b, v0
	v_mul_f32_e32 v176, 0xbfb8aa3b, v176
	v_mul_f32_e32 v180, 0xbfb8aa3b, v180
	v_mul_f32_e32 v177, 0xbfb8aa3b, v177
	v_mul_f32_e32 v181, 0xbfb8aa3b, v181
	v_mul_f32_e32 v188, 0xbfb8aa3b, v178
	v_mul_f32_e32 v189, 0xbfb8aa3b, v182
	v_mul_f32_e32 v190, 0xbfb8aa3b, v179
	v_ashrrev_i32_e32 v219, 31, v218
	v_exp_f32_e32 v182, v0
	v_exp_f32_e32 v183, v176
	v_exp_f32_e32 v184, v180
	v_exp_f32_e32 v185, v177
	v_exp_f32_e32 v178, v181
	v_exp_f32_e32 v179, v188
	v_exp_f32_e32 v180, v189
	v_exp_f32_e32 v181, v190
	v_lshlrev_b64 v[186:187], 11, v[218:219]
	v_lshl_add_u64 v[176:177], s[6:7], 0, v[186:187]
	s_mov_b64 s[64:65], -1
	s_and_b64 vcc, exec, s[42:43]
	v_lshl_add_u64 v[176:177], v[2:3], 1, v[176:177]
	s_cbranch_vccnz .LBB0_292
	v_add_f32_e32 v0, 1.0, v182
	v_rcp_f32_e32 v186, v0
	v_add_f32_e32 v0, 1.0, v183
	v_rcp_f32_e32 v187, v0
	v_add_f32_e32 v0, 1.0, v184
	v_rcp_f32_e32 v188, v0
	v_add_f32_e32 v0, 1.0, v185
	v_rcp_f32_e32 v189, v0
	v_add_f32_e32 v0, 1.0, v178
	v_add_f32_e32 v191, 1.0, v180
	v_rcp_f32_e32 v190, v0
	v_add_f32_e32 v0, 1.0, v179
	v_rcp_f32_e32 v192, v191
	v_add_f32_e32 v191, 1.0, v181
	v_rcp_f32_e32 v193, v191
	v_rcp_f32_e32 v191, v0
	v_pk_mul_f32 v[188:189], v[122:123], v[188:189]
	v_pk_mul_f32 v[186:187], v[120:121], v[186:187]
	v_pk_mul_f32 v[192:193], v[118:119], v[192:193]
	v_pk_mul_f32 v[190:191], v[116:117], v[190:191]
	v_cvt_pk_bf16_f32 v186, v186, v187
	v_cvt_pk_bf16_f32 v187, v188, v189
	v_cvt_pk_bf16_f32 v188, v190, v191
	v_cvt_pk_bf16_f32 v189, v192, v193
	s_mov_b64 s[64:65], 0
	global_store_dwordx4 v[176:177], v[186:189], off
; __device__ __forceinline__ u32x4 pack8(const f32x4 a, const f32x4 b) { u32x4 w; w.x = cvt_pk_bf16(a[0], a[1]); w.y = cvt_pk_bf16(a[2], a[3]); w.z = cvt_pk_bf16(b[0], b[1]); w.w = cvt_pk_bf16(b[2], b[3]); return w; }
; __device__ __forceinline__ void unpack8(const u32x4 w, f32x4& a, f32x4& b) { a = (f32x4){bflo(w.x), bfhi(w.x), bflo(w.y), bfhi(w.y)}; b = (f32x4){bflo(w.z), bfhi(w.z), bflo(w.w), bfhi(w.w)}; }
; __device__ __forceinline__ f32x4 sig4(const f32x4 v) { return (f32x4){sigmoidf_(v[0]), sigmoidf_(v[1]), sigmoidf_(v[2]), sigmoidf_(v[3])}; }
;     __device__ __forceinline__ void operator()(Acc& acc, const Unit& u, int wr, int wc, int fr, int fq) const {
;     ...
;             for (int m = 0; m < 4; ++m)
; #pragma unroll
;                 for (int bj = 0; bj < 2; ++bj) { f32x4 b0, b1; unpack8(bv[m][bj], b0, b1);
;                     if (u.alt == 0) { f32x4 a0, a1; unpack8(av[m][bj], a0, a1);
; #pragma unroll
;                         for (int r = 0; r < 4; ++r) { acc[ai][bj][m][0][r] *= (1.0f + __expf(-b0[r])) * __builtin_amdgcn_rcpf(1.0f + __expf(-a0[r]));
;                                                       acc[ai][bj][m][1][r] *= (1.0f + __expf(-b1[r])) * __builtin_amdgcn_rcpf(1.0f + __expf(-a1[r])); } }
;                     else *(u32x4*)(mixed + (size_t)(row0 + ai * 128 + m * 16) * 1024 + col0 + bj * 128) = pack8(acc[ai][bj][m][0] * sig4(b0), acc[ai][bj][m][1] * sig4(b1)); } }
.LBB0_292:
	s_andn2_b64 vcc, exec, s[64:65]
	s_cbranch_vccnz .LBB0_294
	s_waitcnt vmcnt(6)
	v_lshlrev_b32_e32 v0, 16, v144
	v_lshlrev_b32_e32 v188, 16, v146
	v_mul_f32_e32 v0, 0xbfb8aa3b, v0
	v_and_b32_e32 v186, 0xffff0000, v144
	v_exp_f32_e32 v0, v0
	v_mul_f32_e32 v188, 0xbfb8aa3b, v188
	v_exp_f32_e32 v188, v188
	v_mul_f32_e32 v186, 0xbfb8aa3b, v186
	v_exp_f32_e32 v192, v186
	v_and_b32_e32 v189, 0xffff0000, v146
	v_lshlrev_b32_e32 v187, 16, v145
	v_add_f32_e32 v0, 1.0, v0
	v_mul_f32_e32 v189, 0xbfb8aa3b, v189
	v_lshlrev_b32_e32 v191, 16, v147
	v_rcp_f32_e32 v186, v0
	v_add_f32_e32 v0, 1.0, v188
	v_exp_f32_e32 v189, v189
	v_mul_f32_e32 v187, 0xbfb8aa3b, v187
	v_and_b32_e32 v190, 0xffff0000, v145
	v_rcp_f32_e32 v188, v0
	v_add_f32_e32 v0, 1.0, v192
	v_exp_f32_e32 v192, v187
	v_mul_f32_e32 v191, 0xbfb8aa3b, v191
	v_exp_f32_e32 v191, v191
	v_mul_f32_e32 v190, 0xbfb8aa3b, v190
	v_exp_f32_e32 v194, v190
	v_rcp_f32_e32 v187, v0
	v_add_f32_e32 v0, 1.0, v189
	v_rcp_f32_e32 v189, v0
	v_add_f32_e32 v0, 1.0, v192
	v_rcp_f32_e32 v190, v0
	v_add_f32_e32 v0, 1.0, v191
	v_and_b32_e32 v193, 0xffff0000, v147
	v_rcp_f32_e32 v192, v0
	v_add_f32_e32 v0, 1.0, v194
	v_rcp_f32_e32 v191, v0
	v_mul_f32_e32 v0, 0xbfb8aa3b, v193
	v_exp_f32_e32 v0, v0
	v_pk_add_f32 v[184:185], v[184:185], 1.0 op_sel_hi:[1,0]
	v_pk_add_f32 v[182:183], v[182:183], 1.0 op_sel_hi:[1,0]
	v_pk_add_f32 v[180:181], v[180:181], 1.0 op_sel_hi:[1,0]
	v_add_f32_e32 v0, 1.0, v0
	v_rcp_f32_e32 v193, v0
	v_pk_add_f32 v[178:179], v[178:179], 1.0 op_sel_hi:[1,0]
	v_pk_mul_f32 v[182:183], v[182:183], v[186:187]
	v_pk_mul_f32 v[184:185], v[184:185], v[190:191]
	v_pk_mul_f32 v[178:179], v[178:179], v[188:189]
	v_pk_mul_f32 v[180:181], v[180:181], v[192:193]
	v_pk_mul_f32 v[122:123], v[122:123], v[184:185]
	v_pk_mul_f32 v[120:121], v[120:121], v[182:183]
	v_pk_mul_f32 v[118:119], v[118:119], v[180:181]
	v_pk_mul_f32 v[116:117], v[116:117], v[178:179]
.LBB0_294:
	s_waitcnt vmcnt(5)
	v_lshlrev_b32_e32 v0, 16, v172
	v_and_b32_e32 v172, 0xffff0000, v172
	v_lshlrev_b32_e32 v178, 16, v173
	v_and_b32_e32 v173, 0xffff0000, v173
	v_lshlrev_b32_e32 v179, 16, v174
	v_and_b32_e32 v174, 0xffff0000, v174
	v_lshlrev_b32_e32 v180, 16, v175
	v_and_b32_e32 v175, 0xffff0000, v175
	v_mul_f32_e32 v0, 0xbfb8aa3b, v0
	v_mul_f32_e32 v172, 0xbfb8aa3b, v172
	v_mul_f32_e32 v181, 0xbfb8aa3b, v178
	v_mul_f32_e32 v173, 0xbfb8aa3b, v173
	v_mul_f32_e32 v182, 0xbfb8aa3b, v179
	v_mul_f32_e32 v174, 0xbfb8aa3b, v174
	v_mul_f32_e32 v183, 0xbfb8aa3b, v180
	v_mul_f32_e32 v175, 0xbfb8aa3b, v175
	v_exp_f32_e32 v178, v0
	v_exp_f32_e32 v179, v172
	v_exp_f32_e32 v180, v181
	v_exp_f32_e32 v181, v173
	v_exp_f32_e32 v172, v182
	v_exp_f32_e32 v173, v174
	v_exp_f32_e32 v174, v183
	v_exp_f32_e32 v175, v175
	s_and_b64 vcc, exec, s[42:43]
	s_mov_b64 s[64:65], -1
	s_cbranch_vccnz .LBB0_296
	v_add_f32_e32 v0, 1.0, v178
	v_rcp_f32_e32 v182, v0
	v_add_f32_e32 v0, 1.0, v179
	v_rcp_f32_e32 v183, v0
	v_add_f32_e32 v0, 1.0, v180
	v_rcp_f32_e32 v184, v0
	v_add_f32_e32 v0, 1.0, v181
	v_rcp_f32_e32 v185, v0
	v_add_f32_e32 v0, 1.0, v172
	v_add_f32_e32 v187, 1.0, v174
	v_rcp_f32_e32 v186, v0
	v_add_f32_e32 v0, 1.0, v173
	v_rcp_f32_e32 v188, v187
	v_add_f32_e32 v187, 1.0, v175
	v_rcp_f32_e32 v189, v187
	v_rcp_f32_e32 v187, v0
	v_pk_mul_f32 v[184:185], v[90:91], v[184:185]
	v_pk_mul_f32 v[182:183], v[88:89], v[182:183]
	v_pk_mul_f32 v[188:189], v[86:87], v[188:189]
	v_pk_mul_f32 v[186:187], v[84:85], v[186:187]
	v_cvt_pk_bf16_f32 v182, v182, v183
	v_cvt_pk_bf16_f32 v183, v184, v185
	v_cvt_pk_bf16_f32 v184, v186, v187
	v_cvt_pk_bf16_f32 v185, v188, v189
	s_mov_b64 s[64:65], 0
	global_store_dwordx4 v[176:177], v[182:185], off offset:256
.LBB0_296:
	s_andn2_b64 vcc, exec, s[64:65]
	s_cbranch_vccnz .LBB0_298
	s_waitcnt vmcnt(4)
	v_lshlrev_b32_e32 v0, 16, v140
	v_lshlrev_b32_e32 v182, 16, v142
	v_mul_f32_e32 v0, 0xbfb8aa3b, v0
	v_and_b32_e32 v176, 0xffff0000, v140
	v_exp_f32_e32 v0, v0
	v_mul_f32_e32 v182, 0xbfb8aa3b, v182
	v_exp_f32_e32 v182, v182
	v_mul_f32_e32 v176, 0xbfb8aa3b, v176
	v_exp_f32_e32 v186, v176
	v_and_b32_e32 v183, 0xffff0000, v142
	v_lshlrev_b32_e32 v177, 16, v141
	v_add_f32_e32 v0, 1.0, v0
	v_mul_f32_e32 v183, 0xbfb8aa3b, v183
	v_lshlrev_b32_e32 v185, 16, v143
	v_rcp_f32_e32 v176, v0
	v_add_f32_e32 v0, 1.0, v182
	v_exp_f32_e32 v183, v183
	v_mul_f32_e32 v177, 0xbfb8aa3b, v177
	v_and_b32_e32 v184, 0xffff0000, v141
	v_rcp_f32_e32 v182, v0
	v_add_f32_e32 v0, 1.0, v186
	v_exp_f32_e32 v186, v177
	v_mul_f32_e32 v185, 0xbfb8aa3b, v185
	v_exp_f32_e32 v185, v185
	v_mul_f32_e32 v184, 0xbfb8aa3b, v184
	v_exp_f32_e32 v188, v184
	v_rcp_f32_e32 v177, v0
	v_add_f32_e32 v0, 1.0, v183
	v_rcp_f32_e32 v183, v0
	v_add_f32_e32 v0, 1.0, v186
	v_rcp_f32_e32 v184, v0
	v_add_f32_e32 v0, 1.0, v185
	v_and_b32_e32 v187, 0xffff0000, v143
	v_rcp_f32_e32 v186, v0
	v_add_f32_e32 v0, 1.0, v188
	v_rcp_f32_e32 v185, v0
	v_mul_f32_e32 v0, 0xbfb8aa3b, v187
	v_exp_f32_e32 v0, v0
	v_pk_add_f32 v[180:181], v[180:181], 1.0 op_sel_hi:[1,0]
	v_pk_add_f32 v[178:179], v[178:179], 1.0 op_sel_hi:[1,0]
	v_pk_add_f32 v[174:175], v[174:175], 1.0 op_sel_hi:[1,0]
	v_add_f32_e32 v0, 1.0, v0
	v_rcp_f32_e32 v187, v0
	v_pk_add_f32 v[172:173], v[172:173], 1.0 op_sel_hi:[1,0]
	v_pk_mul_f32 v[176:177], v[178:179], v[176:177]
	v_pk_mul_f32 v[178:179], v[180:181], v[184:185]
	v_pk_mul_f32 v[172:173], v[172:173], v[182:183]
	v_pk_mul_f32 v[174:175], v[174:175], v[186:187]
	v_pk_mul_f32 v[90:91], v[90:91], v[178:179]
	v_pk_mul_f32 v[88:89], v[88:89], v[176:177]
	v_pk_mul_f32 v[86:87], v[86:87], v[174:175]
	v_pk_mul_f32 v[84:85], v[84:85], v[172:173]
; __device__ __forceinline__ u32x4 pack8(const f32x4 a, const f32x4 b) { u32x4 w; w.x = cvt_pk_bf16(a[0], a[1]); w.y = cvt_pk_bf16(a[2], a[3]); w.z = cvt_pk_bf16(b[0], b[1]); w.w = cvt_pk_bf16(b[2], b[3]); return w; }
; __device__ __forceinline__ void unpack8(const u32x4 w, f32x4& a, f32x4& b) { a = (f32x4){bflo(w.x), bfhi(w.x), bflo(w.y), bfhi(w.y)}; b = (f32x4){bflo(w.z), bfhi(w.z), bflo(w.w), bfhi(w.w)}; }
; __device__ __forceinline__ f32x4 sig4(const f32x4 v) { return (f32x4){sigmoidf_(v[0]), sigmoidf_(v[1]), sigmoidf_(v[2]), sigmoidf_(v[3])}; }
;     __device__ __forceinline__ void operator()(Acc& acc, const Unit& u, int wr, int wc, int fr, int fq) const {
;     ...
;                 for (int bj = 0; bj < 2; ++bj) { const size_t off = (size_t)(row0 + ai * 128 + m * 16) * NPROJ + col0 + bj * 128;
;                     bv[m][bj] = *(const u32x4*)(gb + off); if (u.alt == 0) av[m][bj] = *(const u32x4*)(ga + off); }
; #pragma unroll
;             for (int m = 0; m < 4; ++m)
; #pragma unroll
;                 for (int bj = 0; bj < 2; ++bj) { f32x4 b0, b1; unpack8(bv[m][bj], b0, b1);
;                     if (u.alt == 0) { f32x4 a0, a1; unpack8(av[m][bj], a0, a1);
; #pragma unroll
;                         for (int r = 0; r < 4; ++r) { acc[ai][bj][m][0][r] *= (1.0f + __expf(-b0[r])) * __builtin_amdgcn_rcpf(1.0f + __expf(-a0[r]));
;                                                       acc[ai][bj][m][1][r] *= (1.0f + __expf(-b1[r])) * __builtin_amdgcn_rcpf(1.0f + __expf(-a1[r])); } }
;                     else *(u32x4*)(mixed + (size_t)(row0 + ai * 128 + m * 16) * 1024 + col0 + bj * 128) = pack8(acc[ai][bj][m][0] * sig4(b0), acc[ai][bj][m][1] * sig4(b1)); } }
.LBB0_298:
	s_waitcnt vmcnt(3)
	v_lshlrev_b32_e32 v0, 16, v168
	v_and_b32_e32 v168, 0xffff0000, v168
	v_lshlrev_b32_e32 v172, 16, v169
	v_and_b32_e32 v169, 0xffff0000, v169
	v_lshlrev_b32_e32 v173, 16, v170
	v_and_b32_e32 v170, 0xffff0000, v170
	v_lshlrev_b32_e32 v174, 16, v171
	v_and_b32_e32 v171, 0xffff0000, v171
	v_mul_f32_e32 v0, 0xbfb8aa3b, v0
	v_mul_f32_e32 v168, 0xbfb8aa3b, v168
	v_mul_f32_e32 v172, 0xbfb8aa3b, v172
	v_mul_f32_e32 v169, 0xbfb8aa3b, v169
	v_mul_f32_e32 v173, 0xbfb8aa3b, v173
	v_mul_f32_e32 v180, 0xbfb8aa3b, v170
	v_mul_f32_e32 v181, 0xbfb8aa3b, v174
	v_mul_f32_e32 v182, 0xbfb8aa3b, v171
	v_ashrrev_i32_e32 v217, 31, v216
	v_exp_f32_e32 v174, v0
	v_exp_f32_e32 v175, v168
	v_exp_f32_e32 v176, v172
	v_exp_f32_e32 v177, v169
	v_exp_f32_e32 v170, v173
	v_exp_f32_e32 v171, v180
	v_exp_f32_e32 v172, v181
	v_exp_f32_e32 v173, v182
	v_lshlrev_b64 v[178:179], 11, v[216:217]
	v_lshl_add_u64 v[168:169], s[6:7], 0, v[178:179]
	s_mov_b64 s[64:65], -1
	s_and_b64 vcc, exec, s[42:43]
	v_lshl_add_u64 v[168:169], v[2:3], 1, v[168:169]
	s_cbranch_vccnz .LBB0_300
	v_add_f32_e32 v0, 1.0, v174
	v_rcp_f32_e32 v178, v0
	v_add_f32_e32 v0, 1.0, v175
	v_rcp_f32_e32 v179, v0
	v_add_f32_e32 v0, 1.0, v176
	v_rcp_f32_e32 v180, v0
	v_add_f32_e32 v0, 1.0, v177
	v_rcp_f32_e32 v181, v0
	v_add_f32_e32 v0, 1.0, v170
	v_add_f32_e32 v183, 1.0, v172
	v_rcp_f32_e32 v182, v0
	v_add_f32_e32 v0, 1.0, v171
	v_rcp_f32_e32 v184, v183
	v_add_f32_e32 v183, 1.0, v173
	v_rcp_f32_e32 v185, v183
	v_rcp_f32_e32 v183, v0
	v_pk_mul_f32 v[180:181], v[114:115], v[180:181]
	v_pk_mul_f32 v[178:179], v[112:113], v[178:179]
	v_pk_mul_f32 v[184:185], v[110:111], v[184:185]
	v_pk_mul_f32 v[182:183], v[108:109], v[182:183]
	v_cvt_pk_bf16_f32 v178, v178, v179
	v_cvt_pk_bf16_f32 v179, v180, v181
	v_cvt_pk_bf16_f32 v180, v182, v183
	v_cvt_pk_bf16_f32 v181, v184, v185
	s_mov_b64 s[64:65], 0
	global_store_dwordx4 v[168:169], v[178:181], off
.LBB0_300:
	s_andn2_b64 vcc, exec, s[64:65]
	s_cbranch_vccnz .LBB0_302
	s_waitcnt vmcnt(2)
	v_lshlrev_b32_e32 v0, 16, v136
	v_lshlrev_b32_e32 v180, 16, v138
	v_mul_f32_e32 v0, 0xbfb8aa3b, v0
	v_and_b32_e32 v178, 0xffff0000, v136
	v_exp_f32_e32 v0, v0
	v_mul_f32_e32 v180, 0xbfb8aa3b, v180
	v_exp_f32_e32 v180, v180
	v_mul_f32_e32 v178, 0xbfb8aa3b, v178
	v_exp_f32_e32 v184, v178
	v_and_b32_e32 v181, 0xffff0000, v138
	v_lshlrev_b32_e32 v179, 16, v137
	v_add_f32_e32 v0, 1.0, v0
	v_mul_f32_e32 v181, 0xbfb8aa3b, v181
	v_lshlrev_b32_e32 v183, 16, v139
	v_rcp_f32_e32 v178, v0
	v_add_f32_e32 v0, 1.0, v180
	v_exp_f32_e32 v181, v181
	v_mul_f32_e32 v179, 0xbfb8aa3b, v179
	v_and_b32_e32 v182, 0xffff0000, v137
	v_rcp_f32_e32 v180, v0
	v_add_f32_e32 v0, 1.0, v184
	v_exp_f32_e32 v184, v179
	v_mul_f32_e32 v183, 0xbfb8aa3b, v183
	v_exp_f32_e32 v183, v183
	v_mul_f32_e32 v182, 0xbfb8aa3b, v182
	v_exp_f32_e32 v186, v182
	v_rcp_f32_e32 v179, v0
	v_add_f32_e32 v0, 1.0, v181
	v_rcp_f32_e32 v181, v0
	v_add_f32_e32 v0, 1.0, v184
	v_rcp_f32_e32 v182, v0
	v_add_f32_e32 v0, 1.0, v183
	v_and_b32_e32 v185, 0xffff0000, v139
	v_rcp_f32_e32 v184, v0
	v_add_f32_e32 v0, 1.0, v186
	v_rcp_f32_e32 v183, v0
	v_mul_f32_e32 v0, 0xbfb8aa3b, v185
	v_exp_f32_e32 v0, v0
	v_pk_add_f32 v[176:177], v[176:177], 1.0 op_sel_hi:[1,0]
	v_pk_add_f32 v[174:175], v[174:175], 1.0 op_sel_hi:[1,0]
	v_pk_add_f32 v[172:173], v[172:173], 1.0 op_sel_hi:[1,0]
	v_add_f32_e32 v0, 1.0, v0
	v_rcp_f32_e32 v185, v0
	v_pk_add_f32 v[170:171], v[170:171], 1.0 op_sel_hi:[1,0]
	v_pk_mul_f32 v[174:175], v[174:175], v[178:179]
	v_pk_mul_f32 v[176:177], v[176:177], v[182:183]
	v_pk_mul_f32 v[170:171], v[170:171], v[180:181]
	v_pk_mul_f32 v[172:173], v[172:173], v[184:185]
	v_pk_mul_f32 v[114:115], v[114:115], v[176:177]
	v_pk_mul_f32 v[112:113], v[112:113], v[174:175]
	v_pk_mul_f32 v[110:111], v[110:111], v[172:173]
	v_pk_mul_f32 v[108:109], v[108:109], v[170:171]
; __device__ __forceinline__ u32x4 pack8(const f32x4 a, const f32x4 b) { u32x4 w; w.x = cvt_pk_bf16(a[0], a[1]); w.y = cvt_pk_bf16(a[2], a[3]); w.z = cvt_pk_bf16(b[0], b[1]); w.w = cvt_pk_bf16(b[2], b[3]); return w; }
; __device__ __forceinline__ void unpack8(const u32x4 w, f32x4& a, f32x4& b) { a = (f32x4){bflo(w.x), bfhi(w.x), bflo(w.y), bfhi(w.y)}; b = (f32x4){bflo(w.z), bfhi(w.z), bflo(w.w), bfhi(w.w)}; }
; __device__ __forceinline__ f32x4 sig4(const f32x4 v) { return (f32x4){sigmoidf_(v[0]), sigmoidf_(v[1]), sigmoidf_(v[2]), sigmoidf_(v[3])}; }
;     __device__ __forceinline__ void operator()(Acc& acc, const Unit& u, int wr, int wc, int fr, int fq) const {
;     ...
;                 for (int bj = 0; bj < 2; ++bj) { const size_t off = (size_t)(row0 + ai * 128 + m * 16) * NPROJ + col0 + bj * 128;
;                     bv[m][bj] = *(const u32x4*)(gb + off); if (u.alt == 0) av[m][bj] = *(const u32x4*)(ga + off); }
; #pragma unroll
;             for (int m = 0; m < 4; ++m)
; #pragma unroll
;                 for (int bj = 0; bj < 2; ++bj) { f32x4 b0, b1; unpack8(bv[m][bj], b0, b1);
;                     if (u.alt == 0) { f32x4 a0, a1; unpack8(av[m][bj], a0, a1);
; #pragma unroll
;                         for (int r = 0; r < 4; ++r) { acc[ai][bj][m][0][r] *= (1.0f + __expf(-b0[r])) * __builtin_amdgcn_rcpf(1.0f + __expf(-a0[r]));
;                                                       acc[ai][bj][m][1][r] *= (1.0f + __expf(-b1[r])) * __builtin_amdgcn_rcpf(1.0f + __expf(-a1[r])); } }
;                     else *(u32x4*)(mixed + (size_t)(row0 + ai * 128 + m * 16) * 1024 + col0 + bj * 128) = pack8(acc[ai][bj][m][0] * sig4(b0), acc[ai][bj][m][1] * sig4(b1)); } }
.LBB0_302:
	s_waitcnt vmcnt(1)
	v_lshlrev_b32_e32 v0, 16, v164
	v_and_b32_e32 v164, 0xffff0000, v164
	v_lshlrev_b32_e32 v170, 16, v165
	v_and_b32_e32 v165, 0xffff0000, v165
	v_lshlrev_b32_e32 v171, 16, v166
	v_and_b32_e32 v166, 0xffff0000, v166
	v_lshlrev_b32_e32 v172, 16, v167
	v_and_b32_e32 v167, 0xffff0000, v167
	v_mul_f32_e32 v0, 0xbfb8aa3b, v0
	v_mul_f32_e32 v164, 0xbfb8aa3b, v164
	v_mul_f32_e32 v173, 0xbfb8aa3b, v170
	v_mul_f32_e32 v165, 0xbfb8aa3b, v165
	v_mul_f32_e32 v174, 0xbfb8aa3b, v171
	v_mul_f32_e32 v166, 0xbfb8aa3b, v166
	v_mul_f32_e32 v175, 0xbfb8aa3b, v172
	v_mul_f32_e32 v167, 0xbfb8aa3b, v167
	v_exp_f32_e32 v170, v0
	v_exp_f32_e32 v171, v164
	v_exp_f32_e32 v172, v173
	v_exp_f32_e32 v173, v165
	v_exp_f32_e32 v164, v174
	v_exp_f32_e32 v165, v166
	v_exp_f32_e32 v166, v175
	v_exp_f32_e32 v167, v167
	s_and_b64 vcc, exec, s[42:43]
	s_mov_b64 s[64:65], -1
	s_cbranch_vccnz .LBB0_304
	v_add_f32_e32 v0, 1.0, v170
	v_rcp_f32_e32 v174, v0
	v_add_f32_e32 v0, 1.0, v171
	v_rcp_f32_e32 v175, v0
	v_add_f32_e32 v0, 1.0, v172
	v_rcp_f32_e32 v176, v0
	v_add_f32_e32 v0, 1.0, v173
	v_rcp_f32_e32 v177, v0
	v_add_f32_e32 v0, 1.0, v164
	v_add_f32_e32 v179, 1.0, v166
	v_rcp_f32_e32 v178, v0
	v_add_f32_e32 v0, 1.0, v165
	v_rcp_f32_e32 v180, v179
	v_add_f32_e32 v179, 1.0, v167
	v_rcp_f32_e32 v181, v179
	v_rcp_f32_e32 v179, v0
	v_pk_mul_f32 v[176:177], v[82:83], v[176:177]
	v_pk_mul_f32 v[174:175], v[80:81], v[174:175]
	v_pk_mul_f32 v[180:181], v[78:79], v[180:181]
	v_pk_mul_f32 v[178:179], v[76:77], v[178:179]
	v_cvt_pk_bf16_f32 v174, v174, v175
	v_cvt_pk_bf16_f32 v175, v176, v177
	v_cvt_pk_bf16_f32 v176, v178, v179
	v_cvt_pk_bf16_f32 v177, v180, v181
	s_mov_b64 s[64:65], 0
	global_store_dwordx4 v[168:169], v[174:177], off offset:256
.LBB0_304:
	s_andn2_b64 vcc, exec, s[64:65]
	s_cbranch_vccnz .LBB0_306
	s_waitcnt vmcnt(0)
	v_lshlrev_b32_e32 v0, 16, v132
	v_lshlrev_b32_e32 v174, 16, v134
	v_mul_f32_e32 v0, 0xbfb8aa3b, v0
	v_and_b32_e32 v168, 0xffff0000, v132
	v_exp_f32_e32 v0, v0
	v_mul_f32_e32 v174, 0xbfb8aa3b, v174
	v_exp_f32_e32 v174, v174
	v_mul_f32_e32 v168, 0xbfb8aa3b, v168
	v_exp_f32_e32 v178, v168
	v_and_b32_e32 v175, 0xffff0000, v134
	v_lshlrev_b32_e32 v169, 16, v133
	v_add_f32_e32 v0, 1.0, v0
	v_mul_f32_e32 v175, 0xbfb8aa3b, v175
	v_lshlrev_b32_e32 v177, 16, v135
	v_rcp_f32_e32 v168, v0
	v_add_f32_e32 v0, 1.0, v174
	v_exp_f32_e32 v175, v175
	v_mul_f32_e32 v169, 0xbfb8aa3b, v169
	v_and_b32_e32 v176, 0xffff0000, v133
	v_rcp_f32_e32 v174, v0
	v_add_f32_e32 v0, 1.0, v178
	v_exp_f32_e32 v178, v169
	v_mul_f32_e32 v177, 0xbfb8aa3b, v177
	v_exp_f32_e32 v177, v177
	v_mul_f32_e32 v176, 0xbfb8aa3b, v176
	v_exp_f32_e32 v180, v176
	v_rcp_f32_e32 v169, v0
	v_add_f32_e32 v0, 1.0, v175
	v_rcp_f32_e32 v175, v0
	v_add_f32_e32 v0, 1.0, v178
	v_rcp_f32_e32 v176, v0
	v_add_f32_e32 v0, 1.0, v177
	v_and_b32_e32 v179, 0xffff0000, v135
	v_rcp_f32_e32 v178, v0
	v_add_f32_e32 v0, 1.0, v180
	v_rcp_f32_e32 v177, v0
	v_mul_f32_e32 v0, 0xbfb8aa3b, v179
	v_exp_f32_e32 v0, v0
	v_pk_add_f32 v[172:173], v[172:173], 1.0 op_sel_hi:[1,0]
	v_pk_add_f32 v[170:171], v[170:171], 1.0 op_sel_hi:[1,0]
	v_pk_add_f32 v[166:167], v[166:167], 1.0 op_sel_hi:[1,0]
	v_add_f32_e32 v0, 1.0, v0
	v_rcp_f32_e32 v179, v0
	v_pk_add_f32 v[164:165], v[164:165], 1.0 op_sel_hi:[1,0]
	v_pk_mul_f32 v[168:169], v[170:171], v[168:169]
	v_pk_mul_f32 v[170:171], v[172:173], v[176:177]
	v_pk_mul_f32 v[164:165], v[164:165], v[174:175]
	v_pk_mul_f32 v[166:167], v[166:167], v[178:179]
	v_pk_mul_f32 v[82:83], v[82:83], v[170:171]
	v_pk_mul_f32 v[80:81], v[80:81], v[168:169]
	v_pk_mul_f32 v[78:79], v[78:79], v[166:167]
	v_pk_mul_f32 v[76:77], v[76:77], v[164:165]

; __device__ __forceinline__ u32x4 pack8(const f32x4 a, const f32x4 b) { u32x4 w; w.x = cvt_pk_bf16(a[0], a[1]); w.y = cvt_pk_bf16(a[2], a[3]); w.z = cvt_pk_bf16(b[0], b[1]); w.w = cvt_pk_bf16(b[2], b[3]); return w; }
; __device__ __forceinline__ void unpack8(const u32x4 w, f32x4& a, f32x4& b) { a = (f32x4){bflo(w.x), bfhi(w.x), bflo(w.y), bfhi(w.y)}; b = (f32x4){bflo(w.z), bfhi(w.z), bflo(w.w), bfhi(w.w)}; }
; __device__ __forceinline__ f32x4 sig4(const f32x4 v) { return (f32x4){sigmoidf_(v[0]), sigmoidf_(v[1]), sigmoidf_(v[2]), sigmoidf_(v[3])}; }
;     __device__ __forceinline__ void operator()(Acc& acc, const Unit& u, int wr, int wc, int fr, int fq) const {
;     ...
;                 for (int bj = 0; bj < 2; ++bj) { const size_t off = (size_t)(row0 + ai * 128 + m * 16) * NPROJ + col0 + bj * 128;
;                     bv[m][bj] = *(const u32x4*)(gb + off); if (u.alt == 0) av[m][bj] = *(const u32x4*)(ga + off); }
; #pragma unroll
;             for (int m = 0; m < 4; ++m)
; #pragma unroll
;                 for (int bj = 0; bj < 2; ++bj) { f32x4 b0, b1; unpack8(bv[m][bj], b0, b1);
;                     if (u.alt == 0) { f32x4 a0, a1; unpack8(av[m][bj], a0, a1);
; #pragma unroll
;                         for (int r = 0; r < 4; ++r) { acc[ai][bj][m][0][r] *= (1.0f + __expf(-b0[r])) * __builtin_amdgcn_rcpf(1.0f + __expf(-a0[r]));
;                                                       acc[ai][bj][m][1][r] *= (1.0f + __expf(-b1[r])) * __builtin_amdgcn_rcpf(1.0f + __expf(-a1[r])); } }
;                     else *(u32x4*)(mixed + (size_t)(row0 + ai * 128 + m * 16) * 1024 + col0 + bj * 128) = pack8(acc[ai][bj][m][0] * sig4(b0), acc[ai][bj][m][1] * sig4(b1)); } }
.LBB0_314:
	v_ashrrev_i32_e32 v221, 31, v220
	s_waitcnt vmcnt(7)
	v_lshlrev_b32_e32 v0, 16, v192
	v_and_b32_e32 v192, 0xffff0000, v192
	v_lshlrev_b32_e32 v215, 16, v193
	v_and_b32_e32 v193, 0xffff0000, v193
	v_lshlrev_b32_e32 v217, 16, v194
	v_and_b32_e32 v194, 0xffff0000, v194
	v_lshlrev_b32_e32 v219, 16, v195
	v_and_b32_e32 v195, 0xffff0000, v195
	v_lshlrev_b64 v[226:227], 11, v[220:221]
	v_mul_f32_e32 v0, 0xbfb8aa3b, v0
	v_mul_f32_e32 v192, 0xbfb8aa3b, v192
	v_mul_f32_e32 v215, 0xbfb8aa3b, v215
	v_mul_f32_e32 v193, 0xbfb8aa3b, v193
	v_mul_f32_e32 v217, 0xbfb8aa3b, v217
	v_mul_f32_e32 v220, 0xbfb8aa3b, v194
	v_mul_f32_e32 v219, 0xbfb8aa3b, v219
	v_mul_f32_e32 v221, 0xbfb8aa3b, v195
	v_exp_f32_e32 v222, v0
	v_exp_f32_e32 v223, v192
	v_exp_f32_e32 v224, v215
	v_exp_f32_e32 v225, v193
	v_exp_f32_e32 v194, v217
	v_exp_f32_e32 v195, v220
	v_exp_f32_e32 v220, v219
	v_exp_f32_e32 v221, v221
	v_lshl_add_u64 v[192:193], s[6:7], 0, v[226:227]
	s_mov_b64 s[44:45], -1
	s_and_b64 vcc, exec, s[42:43]
	v_lshl_add_u64 v[192:193], v[2:3], 1, v[192:193]
	s_cbranch_vccnz .LBB0_316
	v_add_f32_e32 v0, 1.0, v222
	v_rcp_f32_e32 v226, v0
	v_add_f32_e32 v0, 1.0, v223
	v_rcp_f32_e32 v227, v0
	v_add_f32_e32 v0, 1.0, v224
	v_rcp_f32_e32 v244, v0
	v_add_f32_e32 v0, 1.0, v225
	v_rcp_f32_e32 v245, v0
	v_add_f32_e32 v0, 1.0, v194
	v_add_f32_e32 v215, 1.0, v220
	v_rcp_f32_e32 v246, v0
	v_add_f32_e32 v0, 1.0, v195
	v_rcp_f32_e32 v248, v215
	v_add_f32_e32 v215, 1.0, v221
	v_rcp_f32_e32 v249, v215
	v_rcp_f32_e32 v247, v0
	v_pk_mul_f32 v[250:251], v[74:75], v[244:245]
	v_pk_mul_f32 v[226:227], v[72:73], v[226:227]
	v_pk_mul_f32 v[248:249], v[70:71], v[248:249]
	v_pk_mul_f32 v[246:247], v[68:69], v[246:247]
	v_cvt_pk_bf16_f32 v244, v226, v227
	v_cvt_pk_bf16_f32 v245, v250, v251
	v_cvt_pk_bf16_f32 v246, v246, v247
	v_cvt_pk_bf16_f32 v247, v248, v249
	s_mov_b64 s[44:45], 0
	global_store_dwordx4 v[192:193], v[244:247], off
.LBB0_316:
	s_andn2_b64 vcc, exec, s[44:45]
	s_cbranch_vccnz .LBB0_318
	s_waitcnt vmcnt(14)
	v_lshlrev_b32_e32 v0, 16, v160
	v_lshlrev_b32_e32 v215, 16, v161
	v_and_b32_e32 v217, 0xffff0000, v161
	v_lshlrev_b32_e32 v161, 16, v162
	v_mul_f32_e32 v0, 0xbfb8aa3b, v0
	v_and_b32_e32 v160, 0xffff0000, v160
	v_exp_f32_e32 v0, v0
	v_mul_f32_e32 v161, 0xbfb8aa3b, v161
	v_exp_f32_e32 v161, v161
	v_mul_f32_e32 v160, 0xbfb8aa3b, v160
	v_lshlrev_b32_e32 v226, 16, v163
	v_and_b32_e32 v243, 0xffff0000, v163
	v_exp_f32_e32 v163, v160
	v_and_b32_e32 v219, 0xffff0000, v162
	v_add_f32_e32 v0, 1.0, v0
	v_rcp_f32_e32 v160, v0
	v_add_f32_e32 v0, 1.0, v161
	v_mul_f32_e32 v161, 0xbfb8aa3b, v219
	v_rcp_f32_e32 v162, v0
	v_add_f32_e32 v0, 1.0, v163
	v_exp_f32_e32 v163, v161
	v_mul_f32_e32 v161, 0xbfb8aa3b, v215
	v_exp_f32_e32 v215, v161
	v_rcp_f32_e32 v161, v0
	v_add_f32_e32 v0, 1.0, v163
	v_rcp_f32_e32 v163, v0
	v_add_f32_e32 v0, 1.0, v215
	v_mul_f32_e32 v215, 0xbfb8aa3b, v226
	v_exp_f32_e32 v215, v215
	v_mul_f32_e32 v217, 0xbfb8aa3b, v217
	v_exp_f32_e32 v217, v217
	v_rcp_f32_e32 v226, v0
	v_add_f32_e32 v0, 1.0, v215
	v_rcp_f32_e32 v244, v0
	v_add_f32_e32 v0, 1.0, v217
	v_rcp_f32_e32 v227, v0
	v_mul_f32_e32 v0, 0xbfb8aa3b, v243
	v_exp_f32_e32 v0, v0
	v_pk_add_f32 v[222:223], v[222:223], 1.0 op_sel_hi:[1,0]
	v_pk_add_f32 v[224:225], v[224:225], 1.0 op_sel_hi:[1,0]
	v_pk_mul_f32 v[160:161], v[222:223], v[160:161]
	v_add_f32_e32 v0, 1.0, v0
	v_rcp_f32_e32 v245, v0
	v_pk_mul_f32 v[72:73], v[72:73], v[160:161]
	v_pk_add_f32 v[160:161], v[220:221], 1.0 op_sel_hi:[1,0]
	v_pk_add_f32 v[194:195], v[194:195], 1.0 op_sel_hi:[1,0]
	v_pk_mul_f32 v[222:223], v[224:225], v[226:227]
	v_pk_mul_f32 v[162:163], v[194:195], v[162:163]
	v_pk_mul_f32 v[160:161], v[160:161], v[244:245]
	v_pk_mul_f32 v[74:75], v[74:75], v[222:223]
	v_pk_mul_f32 v[70:71], v[70:71], v[160:161]
	v_pk_mul_f32 v[68:69], v[68:69], v[162:163]
.LBB0_318:
	s_waitcnt vmcnt(7)
	v_lshlrev_b32_e32 v0, 16, v188
	v_and_b32_e32 v160, 0xffff0000, v188
	v_lshlrev_b32_e32 v161, 16, v189
	v_and_b32_e32 v162, 0xffff0000, v189
	v_lshlrev_b32_e32 v163, 16, v190
	v_and_b32_e32 v188, 0xffff0000, v190
	v_lshlrev_b32_e32 v189, 16, v191
	v_and_b32_e32 v190, 0xffff0000, v191
	v_mul_f32_e32 v0, 0xbfb8aa3b, v0
	v_mul_f32_e32 v160, 0xbfb8aa3b, v160
	v_mul_f32_e32 v161, 0xbfb8aa3b, v161
	v_mul_f32_e32 v162, 0xbfb8aa3b, v162
	v_mul_f32_e32 v163, 0xbfb8aa3b, v163
	v_mul_f32_e32 v194, 0xbfb8aa3b, v188
	v_mul_f32_e32 v195, 0xbfb8aa3b, v189
	v_mul_f32_e32 v215, 0xbfb8aa3b, v190
	v_exp_f32_e32 v188, v0
	v_exp_f32_e32 v189, v160
	v_exp_f32_e32 v190, v161
	v_exp_f32_e32 v191, v162
	v_exp_f32_e32 v160, v163
	v_exp_f32_e32 v161, v194
	v_exp_f32_e32 v162, v195
	v_exp_f32_e32 v163, v215
	s_and_b64 vcc, exec, s[42:43]
	s_mov_b64 s[44:45], -1
	s_cbranch_vccnz .LBB0_320
	v_add_f32_e32 v0, 1.0, v188
	v_rcp_f32_e32 v194, v0
	v_add_f32_e32 v0, 1.0, v189
	v_rcp_f32_e32 v195, v0
	v_add_f32_e32 v0, 1.0, v190
	v_rcp_f32_e32 v220, v0
	v_add_f32_e32 v0, 1.0, v191
	v_rcp_f32_e32 v221, v0
	v_add_f32_e32 v0, 1.0, v160
	v_add_f32_e32 v215, 1.0, v162
	v_rcp_f32_e32 v222, v0
	v_add_f32_e32 v0, 1.0, v161
	v_rcp_f32_e32 v224, v215
	v_add_f32_e32 v215, 1.0, v163
	v_rcp_f32_e32 v225, v215
	v_rcp_f32_e32 v223, v0
	v_pk_mul_f32 v[226:227], v[42:43], v[220:221]
	v_pk_mul_f32 v[194:195], v[40:41], v[194:195]
	v_pk_mul_f32 v[224:225], v[38:39], v[224:225]
	v_pk_mul_f32 v[222:223], v[36:37], v[222:223]
	v_cvt_pk_bf16_f32 v220, v194, v195
	v_cvt_pk_bf16_f32 v221, v226, v227
	v_cvt_pk_bf16_f32 v222, v222, v223
	v_cvt_pk_bf16_f32 v223, v224, v225
	s_mov_b64 s[44:45], 0
	global_store_dwordx4 v[192:193], v[220:223], off offset:256
; __device__ __forceinline__ u32x4 pack8(const f32x4 a, const f32x4 b) { u32x4 w; w.x = cvt_pk_bf16(a[0], a[1]); w.y = cvt_pk_bf16(a[2], a[3]); w.z = cvt_pk_bf16(b[0], b[1]); w.w = cvt_pk_bf16(b[2], b[3]); return w; }
; __device__ __forceinline__ void unpack8(const u32x4 w, f32x4& a, f32x4& b) { a = (f32x4){bflo(w.x), bfhi(w.x), bflo(w.y), bfhi(w.y)}; b = (f32x4){bflo(w.z), bfhi(w.z), bflo(w.w), bfhi(w.w)}; }
; __device__ __forceinline__ f32x4 sig4(const f32x4 v) { return (f32x4){sigmoidf_(v[0]), sigmoidf_(v[1]), sigmoidf_(v[2]), sigmoidf_(v[3])}; }
;     __device__ __forceinline__ void operator()(Acc& acc, const Unit& u, int wr, int wc, int fr, int fq) const {
;     ...
;                 for (int bj = 0; bj < 2; ++bj) { const size_t off = (size_t)(row0 + ai * 128 + m * 16) * NPROJ + col0 + bj * 128;
;                     bv[m][bj] = *(const u32x4*)(gb + off); if (u.alt == 0) av[m][bj] = *(const u32x4*)(ga + off); }
; #pragma unroll
;             for (int m = 0; m < 4; ++m)
; #pragma unroll
;                 for (int bj = 0; bj < 2; ++bj) { f32x4 b0, b1; unpack8(bv[m][bj], b0, b1);
;                     if (u.alt == 0) { f32x4 a0, a1; unpack8(av[m][bj], a0, a1);
; #pragma unroll
;                         for (int r = 0; r < 4; ++r) { acc[ai][bj][m][0][r] *= (1.0f + __expf(-b0[r])) * __builtin_amdgcn_rcpf(1.0f + __expf(-a0[r]));
;                                                       acc[ai][bj][m][1][r] *= (1.0f + __expf(-b1[r])) * __builtin_amdgcn_rcpf(1.0f + __expf(-a1[r])); } }
;                     else *(u32x4*)(mixed + (size_t)(row0 + ai * 128 + m * 16) * 1024 + col0 + bj * 128) = pack8(acc[ai][bj][m][0] * sig4(b0), acc[ai][bj][m][1] * sig4(b1)); } }
.LBB0_320:
	s_andn2_b64 vcc, exec, s[44:45]
	s_cbranch_vccnz .LBB0_322
	s_waitcnt vmcnt(12)
	v_lshlrev_b32_e32 v0, 16, v156
	v_lshlrev_b32_e32 v192, 16, v157
	v_and_b32_e32 v193, 0xffff0000, v157
	v_lshlrev_b32_e32 v157, 16, v158
	v_mul_f32_e32 v0, 0xbfb8aa3b, v0
	v_and_b32_e32 v156, 0xffff0000, v156
	v_exp_f32_e32 v0, v0
	v_mul_f32_e32 v157, 0xbfb8aa3b, v157
	v_exp_f32_e32 v157, v157
	v_mul_f32_e32 v156, 0xbfb8aa3b, v156
	v_lshlrev_b32_e32 v195, 16, v159
	v_and_b32_e32 v215, 0xffff0000, v159
	v_exp_f32_e32 v159, v156
	v_and_b32_e32 v194, 0xffff0000, v158
	v_add_f32_e32 v0, 1.0, v0
	v_rcp_f32_e32 v156, v0
	v_add_f32_e32 v0, 1.0, v157
	v_mul_f32_e32 v157, 0xbfb8aa3b, v194
	v_rcp_f32_e32 v158, v0
	v_add_f32_e32 v0, 1.0, v159
	v_exp_f32_e32 v159, v157
	v_mul_f32_e32 v157, 0xbfb8aa3b, v192
	v_exp_f32_e32 v192, v157
	v_rcp_f32_e32 v157, v0
	v_add_f32_e32 v0, 1.0, v159
	v_rcp_f32_e32 v159, v0
	v_add_f32_e32 v0, 1.0, v192
	v_mul_f32_e32 v192, 0xbfb8aa3b, v195
	v_exp_f32_e32 v194, v192
	v_mul_f32_e32 v192, 0xbfb8aa3b, v193
	v_exp_f32_e32 v193, v192
	v_rcp_f32_e32 v192, v0
	v_add_f32_e32 v0, 1.0, v194
	v_rcp_f32_e32 v194, v0
	v_add_f32_e32 v0, 1.0, v193
	v_rcp_f32_e32 v193, v0
	v_mul_f32_e32 v0, 0xbfb8aa3b, v215
	v_exp_f32_e32 v0, v0
	v_pk_add_f32 v[188:189], v[188:189], 1.0 op_sel_hi:[1,0]
	v_pk_add_f32 v[190:191], v[190:191], 1.0 op_sel_hi:[1,0]
	v_pk_mul_f32 v[156:157], v[188:189], v[156:157]
	v_add_f32_e32 v0, 1.0, v0
	v_rcp_f32_e32 v195, v0
	v_pk_mul_f32 v[40:41], v[40:41], v[156:157]
	v_pk_add_f32 v[156:157], v[162:163], 1.0 op_sel_hi:[1,0]
	v_pk_add_f32 v[160:161], v[160:161], 1.0 op_sel_hi:[1,0]
	v_pk_mul_f32 v[188:189], v[190:191], v[192:193]
	v_pk_mul_f32 v[158:159], v[160:161], v[158:159]
	v_pk_mul_f32 v[156:157], v[156:157], v[194:195]
	v_pk_mul_f32 v[42:43], v[42:43], v[188:189]
	v_pk_mul_f32 v[38:39], v[38:39], v[156:157]
	v_pk_mul_f32 v[36:37], v[36:37], v[158:159]
.LBB0_322:
	s_waitcnt vmcnt(7)
	v_lshlrev_b32_e32 v0, 16, v184
	v_and_b32_e32 v158, 0xffff0000, v184
	v_lshlrev_b32_e32 v159, 16, v185
	v_and_b32_e32 v160, 0xffff0000, v185
	v_lshlrev_b32_e32 v161, 16, v186
	v_and_b32_e32 v162, 0xffff0000, v186
	v_lshlrev_b32_e32 v163, 16, v187
	v_and_b32_e32 v184, 0xffff0000, v187
	v_mul_f32_e32 v0, 0xbfb8aa3b, v0
	v_mul_f32_e32 v158, 0xbfb8aa3b, v158
	v_mul_f32_e32 v159, 0xbfb8aa3b, v159
	v_mul_f32_e32 v160, 0xbfb8aa3b, v160
	v_mul_f32_e32 v161, 0xbfb8aa3b, v161
	v_mul_f32_e32 v186, 0xbfb8aa3b, v162
	v_mul_f32_e32 v187, 0xbfb8aa3b, v163
	v_mul_f32_e32 v188, 0xbfb8aa3b, v184
	v_ashrrev_i32_e32 v219, 31, v218
	v_exp_f32_e32 v162, v0
	v_exp_f32_e32 v163, v158
	v_exp_f32_e32 v184, v159
	v_exp_f32_e32 v185, v160
	v_exp_f32_e32 v158, v161
	v_exp_f32_e32 v159, v186
	v_exp_f32_e32 v160, v187
	v_exp_f32_e32 v161, v188
	v_lshlrev_b64 v[156:157], 11, v[218:219]
	v_lshl_add_u64 v[156:157], s[6:7], 0, v[156:157]
	s_mov_b64 s[44:45], -1
	s_and_b64 vcc, exec, s[42:43]
	v_lshl_add_u64 v[156:157], v[2:3], 1, v[156:157]
	s_cbranch_vccnz .LBB0_324
	v_add_f32_e32 v0, 1.0, v162
	v_rcp_f32_e32 v186, v0
	v_add_f32_e32 v0, 1.0, v163
	v_rcp_f32_e32 v187, v0
	v_add_f32_e32 v0, 1.0, v184
	v_rcp_f32_e32 v188, v0
	v_add_f32_e32 v0, 1.0, v185
	v_rcp_f32_e32 v189, v0
	v_add_f32_e32 v0, 1.0, v158
	v_add_f32_e32 v191, 1.0, v160
	v_rcp_f32_e32 v190, v0
	v_add_f32_e32 v0, 1.0, v159
	v_rcp_f32_e32 v192, v191
	v_add_f32_e32 v191, 1.0, v161
	v_rcp_f32_e32 v193, v191
	v_rcp_f32_e32 v191, v0
	v_pk_mul_f32 v[188:189], v[66:67], v[188:189]
	v_pk_mul_f32 v[186:187], v[64:65], v[186:187]
	v_pk_mul_f32 v[192:193], v[62:63], v[192:193]
	v_pk_mul_f32 v[190:191], v[60:61], v[190:191]
	v_cvt_pk_bf16_f32 v186, v186, v187
	v_cvt_pk_bf16_f32 v187, v188, v189
	v_cvt_pk_bf16_f32 v188, v190, v191
	v_cvt_pk_bf16_f32 v189, v192, v193
	s_mov_b64 s[44:45], 0
	global_store_dwordx4 v[156:157], v[186:189], off
.LBB0_324:
	s_andn2_b64 vcc, exec, s[44:45]
	s_cbranch_vccnz .LBB0_326
	s_waitcnt vmcnt(10)
	v_lshlrev_b32_e32 v0, 16, v152
	v_lshlrev_b32_e32 v186, 16, v153
	v_and_b32_e32 v187, 0xffff0000, v153
	v_lshlrev_b32_e32 v153, 16, v154
	v_mul_f32_e32 v0, 0xbfb8aa3b, v0
	v_and_b32_e32 v152, 0xffff0000, v152
	v_exp_f32_e32 v0, v0
	v_mul_f32_e32 v153, 0xbfb8aa3b, v153
	v_exp_f32_e32 v153, v153
	v_mul_f32_e32 v152, 0xbfb8aa3b, v152
	v_lshlrev_b32_e32 v189, 16, v155
	v_and_b32_e32 v190, 0xffff0000, v155
	v_exp_f32_e32 v155, v152
	v_and_b32_e32 v188, 0xffff0000, v154
	v_add_f32_e32 v0, 1.0, v0
	v_rcp_f32_e32 v152, v0
	v_add_f32_e32 v0, 1.0, v153
	v_mul_f32_e32 v153, 0xbfb8aa3b, v188
	v_rcp_f32_e32 v154, v0
	v_add_f32_e32 v0, 1.0, v155
	v_exp_f32_e32 v155, v153
	v_mul_f32_e32 v153, 0xbfb8aa3b, v186
	v_exp_f32_e32 v186, v153
	v_rcp_f32_e32 v153, v0
	v_add_f32_e32 v0, 1.0, v155
	v_rcp_f32_e32 v155, v0
	v_add_f32_e32 v0, 1.0, v186
	v_mul_f32_e32 v186, 0xbfb8aa3b, v189
	v_exp_f32_e32 v188, v186
	v_mul_f32_e32 v186, 0xbfb8aa3b, v187
	v_exp_f32_e32 v187, v186
	v_rcp_f32_e32 v186, v0
	v_add_f32_e32 v0, 1.0, v188
	v_rcp_f32_e32 v188, v0
	v_add_f32_e32 v0, 1.0, v187
	v_rcp_f32_e32 v187, v0
	v_mul_f32_e32 v0, 0xbfb8aa3b, v190
	v_exp_f32_e32 v0, v0
	v_pk_add_f32 v[162:163], v[162:163], 1.0 op_sel_hi:[1,0]
	v_pk_add_f32 v[184:185], v[184:185], 1.0 op_sel_hi:[1,0]
	v_pk_mul_f32 v[152:153], v[162:163], v[152:153]
	v_add_f32_e32 v0, 1.0, v0
	v_rcp_f32_e32 v189, v0
	v_pk_mul_f32 v[64:65], v[64:65], v[152:153]
	v_pk_add_f32 v[152:153], v[160:161], 1.0 op_sel_hi:[1,0]
	v_pk_add_f32 v[158:159], v[158:159], 1.0 op_sel_hi:[1,0]
	v_pk_mul_f32 v[162:163], v[184:185], v[186:187]
	v_pk_mul_f32 v[154:155], v[158:159], v[154:155]
	v_pk_mul_f32 v[152:153], v[152:153], v[188:189]
	v_pk_mul_f32 v[66:67], v[66:67], v[162:163]
	v_pk_mul_f32 v[62:63], v[62:63], v[152:153]
	v_pk_mul_f32 v[60:61], v[60:61], v[154:155]
; __device__ __forceinline__ u32x4 pack8(const f32x4 a, const f32x4 b) { u32x4 w; w.x = cvt_pk_bf16(a[0], a[1]); w.y = cvt_pk_bf16(a[2], a[3]); w.z = cvt_pk_bf16(b[0], b[1]); w.w = cvt_pk_bf16(b[2], b[3]); return w; }
; __device__ __forceinline__ void unpack8(const u32x4 w, f32x4& a, f32x4& b) { a = (f32x4){bflo(w.x), bfhi(w.x), bflo(w.y), bfhi(w.y)}; b = (f32x4){bflo(w.z), bfhi(w.z), bflo(w.w), bfhi(w.w)}; }
; __device__ __forceinline__ f32x4 sig4(const f32x4 v) { return (f32x4){sigmoidf_(v[0]), sigmoidf_(v[1]), sigmoidf_(v[2]), sigmoidf_(v[3])}; }
;     __device__ __forceinline__ void operator()(Acc& acc, const Unit& u, int wr, int wc, int fr, int fq) const {
;     ...
;                 for (int bj = 0; bj < 2; ++bj) { const size_t off = (size_t)(row0 + ai * 128 + m * 16) * NPROJ + col0 + bj * 128;
;                     bv[m][bj] = *(const u32x4*)(gb + off); if (u.alt == 0) av[m][bj] = *(const u32x4*)(ga + off); }
; #pragma unroll
;             for (int m = 0; m < 4; ++m)
; #pragma unroll
;                 for (int bj = 0; bj < 2; ++bj) { f32x4 b0, b1; unpack8(bv[m][bj], b0, b1);
;                     if (u.alt == 0) { f32x4 a0, a1; unpack8(av[m][bj], a0, a1);
; #pragma unroll
;                         for (int r = 0; r < 4; ++r) { acc[ai][bj][m][0][r] *= (1.0f + __expf(-b0[r])) * __builtin_amdgcn_rcpf(1.0f + __expf(-a0[r]));
;                                                       acc[ai][bj][m][1][r] *= (1.0f + __expf(-b1[r])) * __builtin_amdgcn_rcpf(1.0f + __expf(-a1[r])); } }
;                     else *(u32x4*)(mixed + (size_t)(row0 + ai * 128 + m * 16) * 1024 + col0 + bj * 128) = pack8(acc[ai][bj][m][0] * sig4(b0), acc[ai][bj][m][1] * sig4(b1)); } }
.LBB0_326:
	s_waitcnt vmcnt(7)
	v_lshlrev_b32_e32 v0, 16, v180
	v_and_b32_e32 v152, 0xffff0000, v180
	v_lshlrev_b32_e32 v153, 16, v181
	v_and_b32_e32 v154, 0xffff0000, v181
	v_lshlrev_b32_e32 v155, 16, v182
	v_and_b32_e32 v158, 0xffff0000, v182
	v_lshlrev_b32_e32 v159, 16, v183
	v_and_b32_e32 v160, 0xffff0000, v183
	v_mul_f32_e32 v0, 0xbfb8aa3b, v0
	v_mul_f32_e32 v152, 0xbfb8aa3b, v152
	v_mul_f32_e32 v153, 0xbfb8aa3b, v153
	v_mul_f32_e32 v154, 0xbfb8aa3b, v154
	v_mul_f32_e32 v155, 0xbfb8aa3b, v155
	v_mul_f32_e32 v162, 0xbfb8aa3b, v158
	v_mul_f32_e32 v163, 0xbfb8aa3b, v159
	v_mul_f32_e32 v180, 0xbfb8aa3b, v160
	v_exp_f32_e32 v158, v0
	v_exp_f32_e32 v159, v152
	v_exp_f32_e32 v160, v153
	v_exp_f32_e32 v161, v154
	v_exp_f32_e32 v152, v155
	v_exp_f32_e32 v153, v162
	v_exp_f32_e32 v154, v163
	v_exp_f32_e32 v155, v180
	s_and_b64 vcc, exec, s[42:43]
	s_mov_b64 s[44:45], -1
	s_cbranch_vccnz .LBB0_328
	v_add_f32_e32 v0, 1.0, v158
	v_rcp_f32_e32 v162, v0
	v_add_f32_e32 v0, 1.0, v159
	v_rcp_f32_e32 v163, v0
	v_add_f32_e32 v0, 1.0, v160
	v_rcp_f32_e32 v180, v0
	v_add_f32_e32 v0, 1.0, v161
	v_rcp_f32_e32 v181, v0
	v_add_f32_e32 v0, 1.0, v152
	v_add_f32_e32 v183, 1.0, v154
	v_rcp_f32_e32 v182, v0
	v_add_f32_e32 v0, 1.0, v153
	v_rcp_f32_e32 v184, v183
	v_add_f32_e32 v183, 1.0, v155
	v_rcp_f32_e32 v185, v183
	v_rcp_f32_e32 v183, v0
	v_pk_mul_f32 v[186:187], v[34:35], v[180:181]
	v_pk_mul_f32 v[162:163], v[32:33], v[162:163]
	v_pk_mul_f32 v[184:185], v[30:31], v[184:185]
	v_pk_mul_f32 v[182:183], v[28:29], v[182:183]
	v_cvt_pk_bf16_f32 v180, v162, v163
	v_cvt_pk_bf16_f32 v181, v186, v187
	v_cvt_pk_bf16_f32 v182, v182, v183
	v_cvt_pk_bf16_f32 v183, v184, v185
	s_mov_b64 s[44:45], 0
	global_store_dwordx4 v[156:157], v[180:183], off offset:256
.LBB0_328:
	s_andn2_b64 vcc, exec, s[44:45]
	s_cbranch_vccnz .LBB0_330
	s_waitcnt vmcnt(8)
	v_lshlrev_b32_e32 v0, 16, v148
	v_lshlrev_b32_e32 v156, 16, v149
	v_and_b32_e32 v157, 0xffff0000, v149
	v_lshlrev_b32_e32 v149, 16, v150
	v_mul_f32_e32 v0, 0xbfb8aa3b, v0
	v_and_b32_e32 v148, 0xffff0000, v148
	v_exp_f32_e32 v0, v0
	v_mul_f32_e32 v149, 0xbfb8aa3b, v149
	v_exp_f32_e32 v149, v149
	v_mul_f32_e32 v148, 0xbfb8aa3b, v148
	v_lshlrev_b32_e32 v163, 16, v151
	v_and_b32_e32 v180, 0xffff0000, v151
	v_exp_f32_e32 v151, v148
	v_and_b32_e32 v162, 0xffff0000, v150
	v_add_f32_e32 v0, 1.0, v0
	v_rcp_f32_e32 v148, v0
	v_add_f32_e32 v0, 1.0, v149
	v_mul_f32_e32 v149, 0xbfb8aa3b, v162
	v_rcp_f32_e32 v150, v0
	v_add_f32_e32 v0, 1.0, v151
	v_exp_f32_e32 v151, v149
	v_mul_f32_e32 v149, 0xbfb8aa3b, v156
	v_exp_f32_e32 v156, v149
	v_rcp_f32_e32 v149, v0
	v_add_f32_e32 v0, 1.0, v151
	v_rcp_f32_e32 v151, v0
	v_add_f32_e32 v0, 1.0, v156
	v_mul_f32_e32 v156, 0xbfb8aa3b, v163
	v_exp_f32_e32 v162, v156
	v_mul_f32_e32 v156, 0xbfb8aa3b, v157
	v_exp_f32_e32 v157, v156
	v_rcp_f32_e32 v156, v0
	v_add_f32_e32 v0, 1.0, v162
	v_rcp_f32_e32 v162, v0
	v_add_f32_e32 v0, 1.0, v157
	v_rcp_f32_e32 v157, v0
	v_mul_f32_e32 v0, 0xbfb8aa3b, v180
	v_exp_f32_e32 v0, v0
	v_pk_add_f32 v[158:159], v[158:159], 1.0 op_sel_hi:[1,0]
	v_pk_add_f32 v[160:161], v[160:161], 1.0 op_sel_hi:[1,0]
	v_pk_mul_f32 v[148:149], v[158:159], v[148:149]
	v_add_f32_e32 v0, 1.0, v0
	v_rcp_f32_e32 v163, v0
	v_pk_mul_f32 v[32:33], v[32:33], v[148:149]
	v_pk_add_f32 v[148:149], v[154:155], 1.0 op_sel_hi:[1,0]
	v_pk_add_f32 v[152:153], v[152:153], 1.0 op_sel_hi:[1,0]
	v_pk_mul_f32 v[156:157], v[160:161], v[156:157]
	v_pk_mul_f32 v[150:151], v[152:153], v[150:151]
	v_pk_mul_f32 v[148:149], v[148:149], v[162:163]
	v_pk_mul_f32 v[34:35], v[34:35], v[156:157]
	v_pk_mul_f32 v[30:31], v[30:31], v[148:149]
	v_pk_mul_f32 v[28:29], v[28:29], v[150:151]
.LBB0_330:
	s_waitcnt vmcnt(7)
	v_lshlrev_b32_e32 v0, 16, v176
	v_and_b32_e32 v150, 0xffff0000, v176
	v_lshlrev_b32_e32 v151, 16, v177
	v_and_b32_e32 v152, 0xffff0000, v177
	v_lshlrev_b32_e32 v153, 16, v178
	v_and_b32_e32 v154, 0xffff0000, v178
	v_lshlrev_b32_e32 v155, 16, v179
	v_and_b32_e32 v156, 0xffff0000, v179
	v_mul_f32_e32 v0, 0xbfb8aa3b, v0
	v_mul_f32_e32 v150, 0xbfb8aa3b, v150
	v_mul_f32_e32 v151, 0xbfb8aa3b, v151
	v_mul_f32_e32 v152, 0xbfb8aa3b, v152
	v_mul_f32_e32 v153, 0xbfb8aa3b, v153
	v_mul_f32_e32 v158, 0xbfb8aa3b, v154
	v_mul_f32_e32 v159, 0xbfb8aa3b, v155
	v_mul_f32_e32 v160, 0xbfb8aa3b, v156
	v_ashrrev_i32_e32 v217, 31, v216
	v_exp_f32_e32 v154, v0
	v_exp_f32_e32 v155, v150
	v_exp_f32_e32 v156, v151
	v_exp_f32_e32 v157, v152
	v_exp_f32_e32 v150, v153
	v_exp_f32_e32 v151, v158
	v_exp_f32_e32 v152, v159
	v_exp_f32_e32 v153, v160
	v_lshlrev_b64 v[148:149], 11, v[216:217]
	v_lshl_add_u64 v[148:149], s[6:7], 0, v[148:149]
	s_mov_b64 s[44:45], -1
	s_and_b64 vcc, exec, s[42:43]
	v_lshl_add_u64 v[148:149], v[2:3], 1, v[148:149]
	s_cbranch_vccnz .LBB0_332
	v_add_f32_e32 v0, 1.0, v154
	v_rcp_f32_e32 v158, v0
	v_add_f32_e32 v0, 1.0, v155
	v_rcp_f32_e32 v159, v0
	v_add_f32_e32 v0, 1.0, v156
	v_rcp_f32_e32 v160, v0
	v_add_f32_e32 v0, 1.0, v157
	v_rcp_f32_e32 v161, v0
	v_add_f32_e32 v0, 1.0, v150
	v_add_f32_e32 v163, 1.0, v152
	v_rcp_f32_e32 v162, v0
	v_add_f32_e32 v0, 1.0, v151
	v_rcp_f32_e32 v176, v163
	v_add_f32_e32 v163, 1.0, v153
	v_rcp_f32_e32 v177, v163
	v_rcp_f32_e32 v163, v0
	v_pk_mul_f32 v[160:161], v[58:59], v[160:161]
	v_pk_mul_f32 v[158:159], v[56:57], v[158:159]
	v_pk_mul_f32 v[176:177], v[54:55], v[176:177]
	v_pk_mul_f32 v[162:163], v[52:53], v[162:163]
	v_cvt_pk_bf16_f32 v158, v158, v159
	v_cvt_pk_bf16_f32 v159, v160, v161
	v_cvt_pk_bf16_f32 v160, v162, v163
	v_cvt_pk_bf16_f32 v161, v176, v177
	s_mov_b64 s[44:45], 0
	global_store_dwordx4 v[148:149], v[158:161], off
; __device__ __forceinline__ u32x4 pack8(const f32x4 a, const f32x4 b) { u32x4 w; w.x = cvt_pk_bf16(a[0], a[1]); w.y = cvt_pk_bf16(a[2], a[3]); w.z = cvt_pk_bf16(b[0], b[1]); w.w = cvt_pk_bf16(b[2], b[3]); return w; }
; __device__ __forceinline__ void unpack8(const u32x4 w, f32x4& a, f32x4& b) { a = (f32x4){bflo(w.x), bfhi(w.x), bflo(w.y), bfhi(w.y)}; b = (f32x4){bflo(w.z), bfhi(w.z), bflo(w.w), bfhi(w.w)}; }
; __device__ __forceinline__ f32x4 sig4(const f32x4 v) { return (f32x4){sigmoidf_(v[0]), sigmoidf_(v[1]), sigmoidf_(v[2]), sigmoidf_(v[3])}; }
;     __device__ __forceinline__ void operator()(Acc& acc, const Unit& u, int wr, int wc, int fr, int fq) const {
;     ...
;                 for (int bj = 0; bj < 2; ++bj) { const size_t off = (size_t)(row0 + ai * 128 + m * 16) * NPROJ + col0 + bj * 128;
;                     bv[m][bj] = *(const u32x4*)(gb + off); if (u.alt == 0) av[m][bj] = *(const u32x4*)(ga + off); }
; #pragma unroll
;             for (int m = 0; m < 4; ++m)
; #pragma unroll
;                 for (int bj = 0; bj < 2; ++bj) { f32x4 b0, b1; unpack8(bv[m][bj], b0, b1);
;                     if (u.alt == 0) { f32x4 a0, a1; unpack8(av[m][bj], a0, a1);
; #pragma unroll
;                         for (int r = 0; r < 4; ++r) { acc[ai][bj][m][0][r] *= (1.0f + __expf(-b0[r])) * __builtin_amdgcn_rcpf(1.0f + __expf(-a0[r]));
;                                                       acc[ai][bj][m][1][r] *= (1.0f + __expf(-b1[r])) * __builtin_amdgcn_rcpf(1.0f + __expf(-a1[r])); } }
;                     else *(u32x4*)(mixed + (size_t)(row0 + ai * 128 + m * 16) * 1024 + col0 + bj * 128) = pack8(acc[ai][bj][m][0] * sig4(b0), acc[ai][bj][m][1] * sig4(b1)); } }
.LBB0_332:
	s_andn2_b64 vcc, exec, s[44:45]
	s_cbranch_vccnz .LBB0_334
	s_waitcnt vmcnt(6)
	v_lshlrev_b32_e32 v0, 16, v144
	v_lshlrev_b32_e32 v158, 16, v145
	v_and_b32_e32 v159, 0xffff0000, v145
	v_lshlrev_b32_e32 v145, 16, v146
	v_mul_f32_e32 v0, 0xbfb8aa3b, v0
	v_and_b32_e32 v144, 0xffff0000, v144
	v_exp_f32_e32 v0, v0
	v_mul_f32_e32 v145, 0xbfb8aa3b, v145
	v_exp_f32_e32 v145, v145
	v_mul_f32_e32 v144, 0xbfb8aa3b, v144
	v_lshlrev_b32_e32 v161, 16, v147
	v_and_b32_e32 v162, 0xffff0000, v147
	v_exp_f32_e32 v147, v144
	v_and_b32_e32 v160, 0xffff0000, v146
	v_add_f32_e32 v0, 1.0, v0
	v_rcp_f32_e32 v144, v0
	v_add_f32_e32 v0, 1.0, v145
	v_mul_f32_e32 v145, 0xbfb8aa3b, v160
	v_rcp_f32_e32 v146, v0
	v_add_f32_e32 v0, 1.0, v147
	v_exp_f32_e32 v147, v145
	v_mul_f32_e32 v145, 0xbfb8aa3b, v158
	v_exp_f32_e32 v158, v145
	v_rcp_f32_e32 v145, v0
	v_add_f32_e32 v0, 1.0, v147
	v_rcp_f32_e32 v147, v0
	v_add_f32_e32 v0, 1.0, v158
	v_mul_f32_e32 v158, 0xbfb8aa3b, v161
	v_exp_f32_e32 v160, v158
	v_mul_f32_e32 v158, 0xbfb8aa3b, v159
	v_exp_f32_e32 v159, v158
	v_rcp_f32_e32 v158, v0
	v_add_f32_e32 v0, 1.0, v160
	v_rcp_f32_e32 v160, v0
	v_add_f32_e32 v0, 1.0, v159
	v_rcp_f32_e32 v159, v0
	v_mul_f32_e32 v0, 0xbfb8aa3b, v162
	v_exp_f32_e32 v0, v0
	v_pk_add_f32 v[154:155], v[154:155], 1.0 op_sel_hi:[1,0]
	v_pk_add_f32 v[156:157], v[156:157], 1.0 op_sel_hi:[1,0]
	v_pk_mul_f32 v[144:145], v[154:155], v[144:145]
	v_add_f32_e32 v0, 1.0, v0
	v_rcp_f32_e32 v161, v0
	v_pk_mul_f32 v[56:57], v[56:57], v[144:145]
	v_pk_add_f32 v[144:145], v[152:153], 1.0 op_sel_hi:[1,0]
	v_pk_add_f32 v[150:151], v[150:151], 1.0 op_sel_hi:[1,0]
	v_pk_mul_f32 v[154:155], v[156:157], v[158:159]
	v_pk_mul_f32 v[146:147], v[150:151], v[146:147]
	v_pk_mul_f32 v[144:145], v[144:145], v[160:161]
	v_pk_mul_f32 v[58:59], v[58:59], v[154:155]
	v_pk_mul_f32 v[54:55], v[54:55], v[144:145]
	v_pk_mul_f32 v[52:53], v[52:53], v[146:147]
.LBB0_334:
	s_waitcnt vmcnt(5)
	v_lshlrev_b32_e32 v0, 16, v172
	v_and_b32_e32 v144, 0xffff0000, v172
	v_lshlrev_b32_e32 v145, 16, v173
	v_and_b32_e32 v146, 0xffff0000, v173
	v_lshlrev_b32_e32 v147, 16, v174
	v_and_b32_e32 v150, 0xffff0000, v174
	v_lshlrev_b32_e32 v151, 16, v175
	v_and_b32_e32 v152, 0xffff0000, v175
	v_mul_f32_e32 v0, 0xbfb8aa3b, v0
	v_mul_f32_e32 v144, 0xbfb8aa3b, v144
	v_mul_f32_e32 v145, 0xbfb8aa3b, v145
	v_mul_f32_e32 v146, 0xbfb8aa3b, v146
	v_mul_f32_e32 v147, 0xbfb8aa3b, v147
	v_mul_f32_e32 v154, 0xbfb8aa3b, v150
	v_mul_f32_e32 v155, 0xbfb8aa3b, v151
	v_mul_f32_e32 v156, 0xbfb8aa3b, v152
	v_exp_f32_e32 v150, v0
	v_exp_f32_e32 v151, v144
	v_exp_f32_e32 v152, v145
	v_exp_f32_e32 v153, v146
	v_exp_f32_e32 v144, v147
	v_exp_f32_e32 v145, v154
	v_exp_f32_e32 v146, v155
	v_exp_f32_e32 v147, v156
	s_and_b64 vcc, exec, s[42:43]
	s_mov_b64 s[44:45], -1
	s_cbranch_vccnz .LBB0_336
	v_add_f32_e32 v0, 1.0, v150
	v_rcp_f32_e32 v154, v0
	v_add_f32_e32 v0, 1.0, v151
	v_rcp_f32_e32 v155, v0
	v_add_f32_e32 v0, 1.0, v152
	v_rcp_f32_e32 v156, v0
	v_add_f32_e32 v0, 1.0, v153
	v_rcp_f32_e32 v157, v0
	v_add_f32_e32 v0, 1.0, v144
	v_add_f32_e32 v159, 1.0, v146
	v_rcp_f32_e32 v158, v0
	v_add_f32_e32 v0, 1.0, v145
	v_rcp_f32_e32 v160, v159
	v_add_f32_e32 v159, 1.0, v147
	v_rcp_f32_e32 v161, v159
	v_rcp_f32_e32 v159, v0
	v_pk_mul_f32 v[156:157], v[26:27], v[156:157]
	v_pk_mul_f32 v[154:155], v[24:25], v[154:155]
	v_pk_mul_f32 v[160:161], v[22:23], v[160:161]
	v_pk_mul_f32 v[158:159], v[20:21], v[158:159]
	v_cvt_pk_bf16_f32 v154, v154, v155
	v_cvt_pk_bf16_f32 v155, v156, v157
	v_cvt_pk_bf16_f32 v156, v158, v159
	v_cvt_pk_bf16_f32 v157, v160, v161
	s_mov_b64 s[44:45], 0
	global_store_dwordx4 v[148:149], v[154:157], off offset:256
.LBB0_336:
	s_andn2_b64 vcc, exec, s[44:45]
	s_cbranch_vccnz .LBB0_338
	s_waitcnt vmcnt(4)
	v_lshlrev_b32_e32 v0, 16, v140
	v_lshlrev_b32_e32 v148, 16, v141
	v_and_b32_e32 v149, 0xffff0000, v141
	v_lshlrev_b32_e32 v141, 16, v142
	v_mul_f32_e32 v0, 0xbfb8aa3b, v0
	v_and_b32_e32 v140, 0xffff0000, v140
	v_exp_f32_e32 v0, v0
	v_mul_f32_e32 v141, 0xbfb8aa3b, v141
	v_exp_f32_e32 v141, v141
	v_mul_f32_e32 v140, 0xbfb8aa3b, v140
	v_lshlrev_b32_e32 v155, 16, v143
	v_and_b32_e32 v156, 0xffff0000, v143
	v_exp_f32_e32 v143, v140
	v_and_b32_e32 v154, 0xffff0000, v142
	v_add_f32_e32 v0, 1.0, v0
	v_rcp_f32_e32 v140, v0
	v_add_f32_e32 v0, 1.0, v141
	v_mul_f32_e32 v141, 0xbfb8aa3b, v154
	v_rcp_f32_e32 v142, v0
	v_add_f32_e32 v0, 1.0, v143
	v_exp_f32_e32 v143, v141
	v_mul_f32_e32 v141, 0xbfb8aa3b, v148
	v_exp_f32_e32 v148, v141
	v_rcp_f32_e32 v141, v0
	v_add_f32_e32 v0, 1.0, v143
	v_rcp_f32_e32 v143, v0
	v_add_f32_e32 v0, 1.0, v148
	v_mul_f32_e32 v148, 0xbfb8aa3b, v155
	v_exp_f32_e32 v154, v148
	v_mul_f32_e32 v148, 0xbfb8aa3b, v149
	v_exp_f32_e32 v149, v148
	v_rcp_f32_e32 v148, v0
	v_add_f32_e32 v0, 1.0, v154
	v_rcp_f32_e32 v154, v0
	v_add_f32_e32 v0, 1.0, v149
	v_rcp_f32_e32 v149, v0
	v_mul_f32_e32 v0, 0xbfb8aa3b, v156
	v_exp_f32_e32 v0, v0
	v_pk_add_f32 v[150:151], v[150:151], 1.0 op_sel_hi:[1,0]
	v_pk_add_f32 v[152:153], v[152:153], 1.0 op_sel_hi:[1,0]
	v_pk_mul_f32 v[140:141], v[150:151], v[140:141]
	v_add_f32_e32 v0, 1.0, v0
	v_rcp_f32_e32 v155, v0
	v_pk_mul_f32 v[24:25], v[24:25], v[140:141]
	v_pk_add_f32 v[140:141], v[146:147], 1.0 op_sel_hi:[1,0]
	v_pk_add_f32 v[144:145], v[144:145], 1.0 op_sel_hi:[1,0]
	v_pk_mul_f32 v[148:149], v[152:153], v[148:149]
	v_pk_mul_f32 v[142:143], v[144:145], v[142:143]
	v_pk_mul_f32 v[140:141], v[140:141], v[154:155]
	v_pk_mul_f32 v[26:27], v[26:27], v[148:149]
	v_pk_mul_f32 v[22:23], v[22:23], v[140:141]
	v_pk_mul_f32 v[20:21], v[20:21], v[142:143]
; __device__ __forceinline__ u32x4 pack8(const f32x4 a, const f32x4 b) { u32x4 w; w.x = cvt_pk_bf16(a[0], a[1]); w.y = cvt_pk_bf16(a[2], a[3]); w.z = cvt_pk_bf16(b[0], b[1]); w.w = cvt_pk_bf16(b[2], b[3]); return w; }
; __device__ __forceinline__ void unpack8(const u32x4 w, f32x4& a, f32x4& b) { a = (f32x4){bflo(w.x), bfhi(w.x), bflo(w.y), bfhi(w.y)}; b = (f32x4){bflo(w.z), bfhi(w.z), bflo(w.w), bfhi(w.w)}; }
; __device__ __forceinline__ f32x4 sig4(const f32x4 v) { return (f32x4){sigmoidf_(v[0]), sigmoidf_(v[1]), sigmoidf_(v[2]), sigmoidf_(v[3])}; }
;     __device__ __forceinline__ void operator()(Acc& acc, const Unit& u, int wr, int wc, int fr, int fq) const {
;     ...
;                 for (int bj = 0; bj < 2; ++bj) { const size_t off = (size_t)(row0 + ai * 128 + m * 16) * NPROJ + col0 + bj * 128;
;                     bv[m][bj] = *(const u32x4*)(gb + off); if (u.alt == 0) av[m][bj] = *(const u32x4*)(ga + off); }
; #pragma unroll
;             for (int m = 0; m < 4; ++m)
; #pragma unroll
;                 for (int bj = 0; bj < 2; ++bj) { f32x4 b0, b1; unpack8(bv[m][bj], b0, b1);
;                     if (u.alt == 0) { f32x4 a0, a1; unpack8(av[m][bj], a0, a1);
; #pragma unroll
;                         for (int r = 0; r < 4; ++r) { acc[ai][bj][m][0][r] *= (1.0f + __expf(-b0[r])) * __builtin_amdgcn_rcpf(1.0f + __expf(-a0[r]));
;                                                       acc[ai][bj][m][1][r] *= (1.0f + __expf(-b1[r])) * __builtin_amdgcn_rcpf(1.0f + __expf(-a1[r])); } }
;                     else *(u32x4*)(mixed + (size_t)(row0 + ai * 128 + m * 16) * 1024 + col0 + bj * 128) = pack8(acc[ai][bj][m][0] * sig4(b0), acc[ai][bj][m][1] * sig4(b1)); } }
.LBB0_338:
	s_waitcnt vmcnt(3)
	v_lshlrev_b32_e32 v0, 16, v168
	v_and_b32_e32 v140, 0xffff0000, v168
	v_lshlrev_b32_e32 v141, 16, v169
	v_and_b32_e32 v142, 0xffff0000, v169
	v_lshlrev_b32_e32 v143, 16, v170
	v_and_b32_e32 v144, 0xffff0000, v170
	v_lshlrev_b32_e32 v145, 16, v171
	v_and_b32_e32 v146, 0xffff0000, v171
	v_mul_f32_e32 v0, 0xbfb8aa3b, v0
	v_mul_f32_e32 v140, 0xbfb8aa3b, v140
	v_mul_f32_e32 v141, 0xbfb8aa3b, v141
	v_mul_f32_e32 v142, 0xbfb8aa3b, v142
	v_mul_f32_e32 v143, 0xbfb8aa3b, v143
	v_mul_f32_e32 v150, 0xbfb8aa3b, v144
	v_mul_f32_e32 v151, 0xbfb8aa3b, v145
	v_mul_f32_e32 v152, 0xbfb8aa3b, v146
	v_ashrrev_i32_e32 v215, 31, v214
	v_exp_f32_e32 v144, v0
	v_exp_f32_e32 v145, v140
	v_exp_f32_e32 v146, v141
	v_exp_f32_e32 v147, v142
	v_exp_f32_e32 v140, v143
	v_exp_f32_e32 v141, v150
	v_exp_f32_e32 v142, v151
	v_exp_f32_e32 v143, v152
	v_lshlrev_b64 v[148:149], 11, v[214:215]
	v_lshl_add_u64 v[148:149], s[6:7], 0, v[148:149]
	s_mov_b64 s[44:45], -1
	s_and_b64 vcc, exec, s[42:43]
	v_lshl_add_u64 v[2:3], v[2:3], 1, v[148:149]
	s_cbranch_vccnz .LBB0_340
	v_add_f32_e32 v0, 1.0, v144
	v_rcp_f32_e32 v148, v0
	v_add_f32_e32 v0, 1.0, v145
	v_rcp_f32_e32 v149, v0
	v_add_f32_e32 v0, 1.0, v146
	v_rcp_f32_e32 v150, v0
	v_add_f32_e32 v0, 1.0, v147
	v_rcp_f32_e32 v151, v0
	v_add_f32_e32 v0, 1.0, v140
	v_add_f32_e32 v153, 1.0, v142
	v_rcp_f32_e32 v152, v0
	v_add_f32_e32 v0, 1.0, v141
	v_rcp_f32_e32 v154, v153
	v_add_f32_e32 v153, 1.0, v143
	v_rcp_f32_e32 v155, v153
	v_rcp_f32_e32 v153, v0
	v_pk_mul_f32 v[150:151], v[50:51], v[150:151]
	v_pk_mul_f32 v[148:149], v[48:49], v[148:149]
	v_pk_mul_f32 v[154:155], v[46:47], v[154:155]
	v_pk_mul_f32 v[152:153], v[44:45], v[152:153]
	v_cvt_pk_bf16_f32 v148, v148, v149
	v_cvt_pk_bf16_f32 v149, v150, v151
	v_cvt_pk_bf16_f32 v150, v152, v153
	v_cvt_pk_bf16_f32 v151, v154, v155
	s_mov_b64 s[44:45], 0
	global_store_dwordx4 v[2:3], v[148:151], off
.LBB0_340:
	s_andn2_b64 vcc, exec, s[44:45]
	s_cbranch_vccnz .LBB0_342
	s_waitcnt vmcnt(2)
	v_lshlrev_b32_e32 v0, 16, v136
	v_lshlrev_b32_e32 v148, 16, v137
	v_and_b32_e32 v149, 0xffff0000, v137
	v_lshlrev_b32_e32 v137, 16, v138
	v_mul_f32_e32 v0, 0xbfb8aa3b, v0
	v_and_b32_e32 v136, 0xffff0000, v136
	v_exp_f32_e32 v0, v0
	v_mul_f32_e32 v137, 0xbfb8aa3b, v137
	v_exp_f32_e32 v137, v137
	v_mul_f32_e32 v136, 0xbfb8aa3b, v136
	v_lshlrev_b32_e32 v151, 16, v139
	v_and_b32_e32 v152, 0xffff0000, v139
	v_exp_f32_e32 v139, v136
	v_and_b32_e32 v150, 0xffff0000, v138
	v_add_f32_e32 v0, 1.0, v0
	v_rcp_f32_e32 v136, v0
	v_add_f32_e32 v0, 1.0, v137
	v_mul_f32_e32 v137, 0xbfb8aa3b, v150
	v_rcp_f32_e32 v138, v0
	v_add_f32_e32 v0, 1.0, v139
	v_exp_f32_e32 v139, v137
	v_mul_f32_e32 v137, 0xbfb8aa3b, v148
	v_exp_f32_e32 v148, v137
	v_rcp_f32_e32 v137, v0
	v_add_f32_e32 v0, 1.0, v139
	v_rcp_f32_e32 v139, v0
	v_add_f32_e32 v0, 1.0, v148
	v_mul_f32_e32 v148, 0xbfb8aa3b, v151
	v_exp_f32_e32 v150, v148
	v_mul_f32_e32 v148, 0xbfb8aa3b, v149
	v_exp_f32_e32 v149, v148
	v_rcp_f32_e32 v148, v0
	v_add_f32_e32 v0, 1.0, v150
	v_rcp_f32_e32 v150, v0
	v_add_f32_e32 v0, 1.0, v149
	v_rcp_f32_e32 v149, v0
	v_mul_f32_e32 v0, 0xbfb8aa3b, v152
	v_exp_f32_e32 v0, v0
	v_pk_add_f32 v[144:145], v[144:145], 1.0 op_sel_hi:[1,0]
	v_pk_add_f32 v[146:147], v[146:147], 1.0 op_sel_hi:[1,0]
	v_pk_mul_f32 v[136:137], v[144:145], v[136:137]
	v_add_f32_e32 v0, 1.0, v0
	v_rcp_f32_e32 v151, v0
	v_pk_mul_f32 v[48:49], v[48:49], v[136:137]
	v_pk_add_f32 v[136:137], v[142:143], 1.0 op_sel_hi:[1,0]
	v_pk_add_f32 v[140:141], v[140:141], 1.0 op_sel_hi:[1,0]
	v_pk_mul_f32 v[144:145], v[146:147], v[148:149]
	v_pk_mul_f32 v[138:139], v[140:141], v[138:139]
	v_pk_mul_f32 v[136:137], v[136:137], v[150:151]
	v_pk_mul_f32 v[50:51], v[50:51], v[144:145]
	v_pk_mul_f32 v[46:47], v[46:47], v[136:137]
	v_pk_mul_f32 v[44:45], v[44:45], v[138:139]
.LBB0_342:
	s_waitcnt vmcnt(1)
	v_lshlrev_b32_e32 v0, 16, v164
	v_and_b32_e32 v136, 0xffff0000, v164
	v_lshlrev_b32_e32 v137, 16, v165
	v_and_b32_e32 v138, 0xffff0000, v165
	v_lshlrev_b32_e32 v139, 16, v166
	v_and_b32_e32 v140, 0xffff0000, v166
	v_lshlrev_b32_e32 v141, 16, v167
	v_and_b32_e32 v142, 0xffff0000, v167
	v_mul_f32_e32 v0, 0xbfb8aa3b, v0
	v_mul_f32_e32 v136, 0xbfb8aa3b, v136
	v_mul_f32_e32 v137, 0xbfb8aa3b, v137
	v_mul_f32_e32 v138, 0xbfb8aa3b, v138
	v_mul_f32_e32 v139, 0xbfb8aa3b, v139
	v_mul_f32_e32 v144, 0xbfb8aa3b, v140
	v_mul_f32_e32 v145, 0xbfb8aa3b, v141
	v_mul_f32_e32 v146, 0xbfb8aa3b, v142
	v_exp_f32_e32 v140, v0
	v_exp_f32_e32 v141, v136
	v_exp_f32_e32 v142, v137
	v_exp_f32_e32 v143, v138
	v_exp_f32_e32 v136, v139
	v_exp_f32_e32 v137, v144
	v_exp_f32_e32 v138, v145
	v_exp_f32_e32 v139, v146
	s_and_b64 vcc, exec, s[42:43]
	s_mov_b64 s[44:45], -1
	s_cbranch_vccnz .LBB0_345
	v_add_f32_e32 v0, 1.0, v140
	v_rcp_f32_e32 v144, v0
	v_add_f32_e32 v0, 1.0, v141
	v_rcp_f32_e32 v145, v0
	v_add_f32_e32 v0, 1.0, v142
	v_rcp_f32_e32 v146, v0
	v_add_f32_e32 v0, 1.0, v143
	v_rcp_f32_e32 v147, v0
	v_add_f32_e32 v0, 1.0, v136
	v_add_f32_e32 v149, 1.0, v138
	v_rcp_f32_e32 v148, v0
	v_add_f32_e32 v0, 1.0, v137
	v_rcp_f32_e32 v150, v149
	v_add_f32_e32 v149, 1.0, v139
	v_rcp_f32_e32 v151, v149
	v_rcp_f32_e32 v149, v0
	v_pk_mul_f32 v[146:147], v[18:19], v[146:147]
	v_pk_mul_f32 v[144:145], v[16:17], v[144:145]
	v_pk_mul_f32 v[150:151], v[14:15], v[150:151]
	v_pk_mul_f32 v[148:149], v[12:13], v[148:149]
	v_cvt_pk_bf16_f32 v144, v144, v145
	v_cvt_pk_bf16_f32 v145, v146, v147
	v_cvt_pk_bf16_f32 v146, v148, v149
	v_cvt_pk_bf16_f32 v147, v150, v151
	global_store_dwordx4 v[2:3], v[144:147], off offset:256
	s_cbranch_execz .LBB0_346

; __device__ __forceinline__ u32x4 pack8(const f32x4 a, const f32x4 b) { u32x4 w; w.x = cvt_pk_bf16(a[0], a[1]); w.y = cvt_pk_bf16(a[2], a[3]); w.z = cvt_pk_bf16(b[0], b[1]); w.w = cvt_pk_bf16(b[2], b[3]); return w; }
; __device__ __forceinline__ void unpack8(const u32x4 w, f32x4& a, f32x4& b) { a = (f32x4){bflo(w.x), bfhi(w.x), bflo(w.y), bfhi(w.y)}; b = (f32x4){bflo(w.z), bfhi(w.z), bflo(w.w), bfhi(w.w)}; }
; __device__ __forceinline__ f32x4 sig4(const f32x4 v) { return (f32x4){sigmoidf_(v[0]), sigmoidf_(v[1]), sigmoidf_(v[2]), sigmoidf_(v[3])}; }
;     __device__ __forceinline__ void operator()(Acc& acc, const Unit& u, int wr, int wc, int fr, int fq) const {
;     ...
;                 for (int bj = 0; bj < 2; ++bj) { const size_t off = (size_t)(row0 + ai * 128 + m * 16) * NPROJ + col0 + bj * 128;
;                     bv[m][bj] = *(const u32x4*)(gb + off); if (u.alt == 0) av[m][bj] = *(const u32x4*)(ga + off); }
; #pragma unroll
;             for (int m = 0; m < 4; ++m)
; #pragma unroll
;                 for (int bj = 0; bj < 2; ++bj) { f32x4 b0, b1; unpack8(bv[m][bj], b0, b1);
;                     if (u.alt == 0) { f32x4 a0, a1; unpack8(av[m][bj], a0, a1);
; #pragma unroll
;                         for (int r = 0; r < 4; ++r) { acc[ai][bj][m][0][r] *= (1.0f + __expf(-b0[r])) * __builtin_amdgcn_rcpf(1.0f + __expf(-a0[r]));
;                                                       acc[ai][bj][m][1][r] *= (1.0f + __expf(-b1[r])) * __builtin_amdgcn_rcpf(1.0f + __expf(-a1[r])); } }
;                     else *(u32x4*)(mixed + (size_t)(row0 + ai * 128 + m * 16) * 1024 + col0 + bj * 128) = pack8(acc[ai][bj][m][0] * sig4(b0), acc[ai][bj][m][1] * sig4(b1)); } }
.LBB0_346:
	s_waitcnt vmcnt(0)
	v_lshlrev_b32_e32 v0, 16, v132
	v_and_b32_e32 v2, 0xffff0000, v132
	v_lshlrev_b32_e32 v132, 16, v134
	v_mul_f32_e32 v0, 0xbfb8aa3b, v0
	v_exp_f32_e32 v0, v0
	v_mul_f32_e32 v132, 0xbfb8aa3b, v132
	v_exp_f32_e32 v132, v132
	v_mul_f32_e32 v2, 0xbfb8aa3b, v2
	v_lshlrev_b32_e32 v3, 16, v133
	v_and_b32_e32 v144, 0xffff0000, v133
	v_and_b32_e32 v133, 0xffff0000, v134
	v_lshlrev_b32_e32 v134, 16, v135
	v_and_b32_e32 v145, 0xffff0000, v135
	v_exp_f32_e32 v135, v2
	v_add_f32_e32 v0, 1.0, v0
	v_mul_f32_e32 v133, 0xbfb8aa3b, v133
	v_rcp_f32_e32 v2, v0
	v_add_f32_e32 v0, 1.0, v132
	v_exp_f32_e32 v133, v133
	v_mul_f32_e32 v3, 0xbfb8aa3b, v3
	v_rcp_f32_e32 v132, v0
	v_add_f32_e32 v0, 1.0, v135
	v_exp_f32_e32 v135, v3
	v_rcp_f32_e32 v3, v0
	v_add_f32_e32 v0, 1.0, v133
	v_mul_f32_e32 v134, 0xbfb8aa3b, v134
	v_rcp_f32_e32 v133, v0
	v_add_f32_e32 v0, 1.0, v135
	v_exp_f32_e32 v135, v134
	v_mul_f32_e32 v134, 0xbfb8aa3b, v144
	v_exp_f32_e32 v146, v134
	v_rcp_f32_e32 v134, v0
	v_add_f32_e32 v0, 1.0, v135
	v_rcp_f32_e32 v144, v0
	v_add_f32_e32 v0, 1.0, v146
	v_rcp_f32_e32 v135, v0
	v_mul_f32_e32 v0, 0xbfb8aa3b, v145
	v_exp_f32_e32 v0, v0
	v_pk_add_f32 v[142:143], v[142:143], 1.0 op_sel_hi:[1,0]
	v_pk_add_f32 v[140:141], v[140:141], 1.0 op_sel_hi:[1,0]
	v_pk_mul_f32 v[134:135], v[142:143], v[134:135]
	v_add_f32_e32 v0, 1.0, v0
	v_rcp_f32_e32 v145, v0
	v_pk_mul_f32 v[2:3], v[140:141], v[2:3]
	v_pk_mul_f32 v[18:19], v[18:19], v[134:135]
	v_pk_mul_f32 v[16:17], v[16:17], v[2:3]
	v_pk_add_f32 v[2:3], v[138:139], 1.0 op_sel_hi:[1,0]
	v_pk_add_f32 v[134:135], v[136:137], 1.0 op_sel_hi:[1,0]
	v_pk_mul_f32 v[2:3], v[2:3], v[144:145]
	v_pk_mul_f32 v[132:133], v[134:135], v[132:133]
	v_pk_mul_f32 v[14:15], v[14:15], v[2:3]
	v_pk_mul_f32 v[12:13], v[12:13], v[132:133]
	s_mov_b64 s[44:45], -1
	s_and_b64 vcc, exec, s[40:41]
	s_cbranch_vccz .LBB0_253
